# scan: right-looking f32 triangular solve on transposed A (fewer dependent ops), consts hoisted out of chunk loop
# speedup vs baseline: 1.0204x; 1.0204x over previous
; #define MFMA(a, b, c) __builtin_amdgcn_mfma_f32_32x32x16_f16((a), (b), (c), 0, 0, 0)
; DI void scan_chain_c(const P& p, int l, int chain, char* smem, const XcdBarrier* xb, const int* hint, int nhs) {
;     ...
;     {
;       f32x16 acc;
; #pragma unroll
;       for (int i = 0; i < 16; ++i) acc[i] = 0.f;
; #pragma unroll
;       for (int ks = 0; ks < 4; ++ks) acc = MFMA(__builtin_bit_cast(h16x8, af[ks]), bf[ks], acc);
;       float* rw = raw + mat * 2048 + nblk * 32 + r;
; #pragma unroll
;       for (int i = 0; i < 16; ++i) rw[(4 * hh + (i & 3) + 8 * (i >> 2)) * 64] = acc[i];
;     }
;     __syncthreads();
;     const int arrived = *sflag;
;     float lw[8], kkv[8], bbv[8], kmv[8], rrv[8], vvv[8], cl[8];
;     float run = 0.f;
;     const int cc = h * 64 + lane;
;     const float w0 = p.in[I_W0][(l * 2 + d) * 512 + cc], a0 = p.in[I_A0][(l * 2 + d) * 512 + cc];
;     const float kkc = p.in[I_KK][l * 512 + cc], kac = p.in[I_KA][l * 512 + cc], rkc = p.in[I_RK][l * 512 + cc];
;     const float trA = cvp[(d ? 3072 : 0) + cc], tr1 = cvp[1536 + cc], trC = cvp[(d ? 0 : 3072) + cc];
;     const float tkA = cvp[(d ? 3072 : 0) + 512 + cc], tk1 = cvp[1536 + 512 + cc], tkC = cvp[(d ? 0 : 3072) + 512 + cc];
;     const float tvA = cvp[(d ? 3072 : 0) + 1024 + cc], tv1 = cvp[1536 + 1024 + cc], tvC = cvp[(d ? 0 : 3072) + 1024 + cc];
.LBB0_2335:
	s_or_b64 exec, exec, s[0:1]
	s_waitcnt vmcnt(3)
	v_mfma_f32_32x32x16_f16 v[18:33], v[50:53], v[34:37], 0
	v_ashrrev_i32_e32 v150, 5, v80
	v_and_b32_e32 v148, 31, v80
	v_lshlrev_b32_e32 v77, 2, v150
	v_lshl_add_u32 v0, v148, 2, v112
	v_lshlrev_b32_e32 v164, 10, v150
	v_or_b32_e32 v179, 1, v77
	v_or_b32_e32 v178, 2, v77
	s_waitcnt vmcnt(2)
	v_mfma_f32_32x32x16_f16 v[18:33], v[54:57], v[38:41], v[18:33]
	v_or_b32_e32 v177, 3, v77
	v_add_u32_e32 v176, 8, v77
	v_add_u32_e32 v175, 9, v77
	v_add_u32_e32 v174, 10, v77
	v_add_u32_e32 v76, v0, v164
	v_lshlrev_b32_e32 v163, 8, v179
	v_lshlrev_b32_e32 v162, 8, v178
	s_waitcnt vmcnt(1)
	v_mfma_f32_32x32x16_f16 v[18:33], v[58:61], v[42:45], v[18:33]
	v_lshlrev_b32_e32 v161, 8, v177
	v_lshlrev_b32_e32 v160, 8, v176
	v_lshlrev_b32_e32 v159, 8, v175
	v_lshlrev_b32_e32 v157, 8, v174
	v_add_u32_e32 v173, 11, v77
	v_add_u32_e32 v78, v0, v163
	v_add_u32_e32 v81, v0, v162
	s_waitcnt vmcnt(0)
	v_mfma_f32_32x32x16_f16 v[18:33], v[62:65], v[46:49], v[18:33]
	v_add_u32_e32 v82, v0, v161
	v_add_u32_e32 v83, v0, v160
	v_add_u32_e32 v149, v0, v159
	v_lshlrev_b32_e32 v158, 8, v173
	v_add_u32_e32 v172, 16, v77
	v_lshlrev_b32_e32 v156, 8, v172
	v_add_u32_e32 v171, 17, v77
	s_nop 4
	ds_write_b32 v76, v18
	ds_write_b32 v78, v19
	ds_write_b32 v81, v20
	ds_write_b32 v82, v21
	ds_write_b32 v83, v22
	ds_write_b32 v149, v23
	v_add_u32_e32 v18, v0, v157
	ds_write_b32 v18, v24
	v_add_u32_e32 v18, v0, v158
	ds_write_b32 v18, v25
	v_add_u32_e32 v18, v0, v156
	v_lshlrev_b32_e32 v155, 8, v171
	v_add_u32_e32 v170, 18, v77
	ds_write_b32 v18, v26
	v_add_u32_e32 v18, v0, v155
	v_lshlrev_b32_e32 v154, 8, v170
	v_add_u32_e32 v169, 19, v77
	ds_write_b32 v18, v27
	v_add_u32_e32 v18, v0, v154
	v_lshlrev_b32_e32 v153, 8, v169
	v_add_u32_e32 v168, 24, v77
	ds_write_b32 v18, v28
	v_add_u32_e32 v18, v0, v153
	v_lshlrev_b32_e32 v81, 8, v168
	v_add_u32_e32 v167, 25, v77
	ds_write_b32 v18, v29
	v_add_u32_e32 v18, v0, v81
	v_lshlrev_b32_e32 v82, 8, v167
	v_add_u32_e32 v166, 26, v77
	ds_write_b32 v18, v30
	v_add_u32_e32 v18, v0, v82
	v_lshlrev_b32_e32 v83, 8, v166
	ds_write_b32 v18, v31
	v_add_u32_e32 v18, v0, v83
	ds_write_b32 v18, v32
	v_add_u32_e32 v18, s33, v80
	v_add_u32_e32 v20, s78, v18
	v_add_u32_e32 v165, 27, v77
	v_ashrrev_i32_e32 v21, 31, v20
	v_readlane_b32 s52, v252, 33
	v_lshlrev_b32_e32 v152, 8, v165
	v_lshlrev_b64 v[20:21], 2, v[20:21]
	v_readlane_b32 s60, v252, 41
	v_readlane_b32 s61, v252, 42
	v_add_u32_e32 v0, v0, v152
	ds_write_b32 v0, v33
	v_lshl_add_u64 v[22:23], s[60:61], 0, v[20:21]
	s_waitcnt lgkmcnt(0)
	s_barrier
	s_movk_i32 s0, 0x1000
	s_mov_b32 s11, s37
	s_mov_b64 s[26:27], s[90:91]
	s_mov_b64 s[18:19], s[94:95]
	s_mov_b64 s[16:17], s[92:93]
	v_readlane_b32 s66, v252, 47
	v_readlane_b32 s67, v252, 48
	v_readlane_b32 s80, v253, 4
	v_readlane_b32 s81, v253, 5
	v_readlane_b32 s82, v253, 6
	v_readlane_b32 s83, v253, 7
	v_readlane_b32 s56, v252, 37
	v_readlane_b32 s57, v252, 38
	s_cmp_lg_u32 s25, 0
	s_cbranch_scc1 .Lscan_consts_ready
	global_load_dword v220, v[22:23], off
	v_add_u32_e32 v24, s71, v18
	v_ashrrev_i32_e32 v19, 31, v18
	v_ashrrev_i32_e32 v25, 31, v24
	v_lshl_add_u64 v[30:31], v[18:19], 2, s[4:5]
	v_lshl_add_u64 v[28:29], v[24:25], 2, s[4:5]
	v_add_co_u32_e32 v32, vcc, s0, v30
	s_nop 1
	v_addc_co_u32_e32 v33, vcc, 0, v31, vcc
	v_lshl_add_u64 v[180:181], v[30:31], 0, s[10:11]
	global_load_dword v221, v[28:29], off
	global_load_dword v222, v[32:33], off offset:2048
	global_load_dword v223, v[180:181], off
	v_add_u32_e32 v28, s2, v18
	v_add_u32_e32 v22, s3, v18
	v_ashrrev_i32_e32 v29, 31, v28
	v_add_u32_e32 v24, 0x400, v24
	v_lshl_add_u64 v[32:33], v[28:29], 2, s[4:5]
	v_add_co_u32_e32 v28, vcc, s15, v30
	v_add_u32_e32 v30, s77, v18
	v_ashrrev_i32_e32 v25, 31, v24
	v_ashrrev_i32_e32 v23, 31, v22
	v_addc_co_u32_e32 v29, vcc, 0, v31, vcc
	v_ashrrev_i32_e32 v31, 31, v30
	v_lshl_add_u64 v[24:25], v[24:25], 2, s[4:5]
	v_lshlrev_b64 v[22:23], 2, v[22:23]
	v_lshl_add_u64 v[30:31], v[30:31], 2, s[4:5]
	global_load_dword v228, v[28:29], off
	global_load_dword v229, v[30:31], off
	global_load_dword v230, v[24:25], off
	global_load_dword v231, v[28:29], off offset:2048
	global_load_dword v232, v[32:33], off
	v_lshl_add_u64 v[24:25], s[66:67], 0, v[22:23]
	global_load_dword v233, v[24:25], off
	v_lshl_add_u64 v[24:25], s[80:81], 0, v[22:23]
	global_load_dword v234, v[24:25], off
	v_add_u32_e32 v18, s24, v18
	v_lshl_add_u64 v[22:23], s[82:83], 0, v[22:23]
	global_load_dword v235, v[22:23], off
	v_ashrrev_i32_e32 v19, 31, v18
	v_lshl_add_u64 v[18:19], v[18:19], 2, s[4:5]
	v_lshl_add_u64 v[20:21], s[56:57], 0, v[20:21]
	global_load_dword v236, v[20:21], off
	global_load_dword v237, v[18:19], off
	s_waitcnt vmcnt(0)
; DI float sigmoidf_(float x) { return __builtin_amdgcn_rcpf(1.f + __expf(-x)); }
; #define L(ph, l, hf) hipLaunchKernelGGL(k_phase<ph>, dim3(G), dim3(256), 0, stream, p, l, hf)
; DI void scan_chain_c(const P& p, int l, int chain, char* smem, const XcdBarrier* xb, const int* hint, int nhs) {
;     ...
;     float lw[8], kkv[8], bbv[8], kmv[8], rrv[8], vvv[8], cl[8];
;     float run = 0.f;
;     const int cc = h * 64 + lane;
;     const float w0 = p.in[I_W0][(l * 2 + d) * 512 + cc], a0 = p.in[I_A0][(l * 2 + d) * 512 + cc];
;     const float kkc = p.in[I_KK][l * 512 + cc], kac = p.in[I_KA][l * 512 + cc], rkc = p.in[I_RK][l * 512 + cc];
;     const float trA = cvp[(d ? 3072 : 0) + cc], tr1 = cvp[1536 + cc], trC = cvp[(d ? 0 : 3072) + cc];
;     const float tkA = cvp[(d ? 3072 : 0) + 512 + cc], tk1 = cvp[1536 + 512 + cc], tkC = cvp[(d ? 0 : 3072) + 512 + cc];
;     const float tvA = cvp[(d ? 3072 : 0) + 1024 + cc], tv1 = cvp[1536 + 1024 + cc], tvC = cvp[(d ? 0 : 3072) + 1024 + cc];
; #pragma unroll
;     for (int e = 0; e < 8; ++e) {
;       const int tt = 8 * w + e;
;       const int n = nn + tt;
;       const int pos = d ? (L - 1 - n) : n;
;       const size_t row = (size_t)rowbase + pos;
;       const float rr = trA * (float)xr[e] + tr1 * (float)xr[e + 1] + trC * (float)xr[e + 2];
;       const float kx = tkA * (float)xk[e] + tk1 * (float)xk[e + 1] + tkC * (float)xk[e + 2];
;       const float vv = tvA * (float)xv[e] + tv1 * (float)xv[e + 1] + tvC * (float)xv[e + 2];
;       const float wr = w0 + raw[tt * 64 + lane], ar = a0 + raw[2048 + tt * 64 + lane];
;       const float z = -wr;
;       const float sp = fmaxf(z, 0.f) + __logf(1.f + __expf(-fabsf(z)));
;       const float lgw = -__expf(-sp - 0.5f);
;       const float aa = sigmoidf_(ar);
;       const float kkr = kx * kkc;
;       const float kkn = kkr * __builtin_amdgcn_rsqf(fmaxf(wave_sum(kkr * kkr), 1e-24f));
;       const float km = kx * (1.f + (aa - 1.f) * kac);
;       const float bon = wave_sum(rr * km * rkc);
;       if (lane == 0) bs[((size_t)d * TA + row) * 8 + h] = bon;
.Lscan_consts_ready:
	v_mov_b32_e32 v26, v220
	v_mov_b32_e32 v197, v221
	v_mov_b32_e32 v208, v222
	v_mov_b32_e32 v207, v223
	v_mov_b32_e32 v214, v228
	v_mov_b32_e32 v213, v229
	v_mov_b32_e32 v0, v230
	v_mov_b32_e32 v28, v231
	v_mov_b32_e32 v215, v232
	v_mov_b32_e32 v206, v233
	v_mov_b32_e32 v201, v234
	v_mov_b32_e32 v200, v235
	v_mov_b32_e32 v25, v236
	v_mov_b32_e32 v29, v237
	v_lshlrev_b32_e32 v24, 2, v80
	v_mov_b32_e32 v18, 0x11ff4
	v_lshl_add_u32 v19, v122, 2, v24
	ds_read_b32 v149, v18
	v_add_u32_e32 v20, v74, v24
	ds_read_b32 v27, v19
	ds_read_b32 v19, v20 offset:8192
	v_cvt_f32_f16_e32 v18, v87
	s_cmpk_gt_u32 s25, 0xff
	s_cselect_b32 s7, s0, 0x100
	s_cselect_b32 s36, s70, s31
	s_add_i32 s0, s25, 0xffffff00
	s_min_u32 s11, s0, s25
	v_readlane_b32 s65, v252, 46
	s_add_u32 s0, s23, s36
	s_movk_i32 s65, 0x1000
	v_cmp_eq_u32_e32 vcc, 0, v80
	s_addc_u32 s1, s22, 0
	v_readlane_b32 s53, v252, 34
	v_readlane_b32 s54, v252, 35
	v_readlane_b32 s55, v252, 36
	v_readlane_b32 s58, v252, 39
	v_readlane_b32 s59, v252, 40
	v_readlane_b32 s62, v252, 43
	v_readlane_b32 s63, v252, 44
	v_readlane_b32 s64, v252, 45
	v_readlane_b32 s84, v253, 8
	s_waitcnt lgkmcnt(0)
	v_add_f32_e32 v19, v26, v19
	v_mul_f32_e32 v19, 0xbfb8aa3b, v19
	v_exp_f32_e32 v19, v19
	v_readlane_b32 s85, v253, 9
	v_readlane_b32 s86, v253, 10
	v_readlane_b32 s87, v253, 11
	v_add_f32_e32 v19, 1.0, v19
	v_rcp_f32_e32 v32, v19
	v_readlane_b32 s88, v253, 12
	v_readlane_b32 s89, v253, 13
	v_readlane_b32 s90, v253, 14
	v_add_f32_e32 v23, -1.0, v32
	v_mul_f32_e32 v20, v208, v18
	v_fma_mix_f32 v20, v197, v88, v20 op_sel_hi:[0,1,0]
	v_fma_mix_f32 v30, v207, v94, v20 op_sel_hi:[0,1,0]
	v_cvt_f32_f16_e32 v20, v91
	v_readlane_b32 s91, v253, 15
	v_readlane_b32 s92, v253, 16
	v_readlane_b32 s93, v253, 17
	v_readlane_b32 s94, v253, 18
	v_readlane_b32 s95, v253, 19
	v_mul_f32_e32 v21, v214, v20
	v_fma_mix_f32 v21, v215, v89, v21 op_sel_hi:[0,1,0]
	v_fma_mix_f32 v21, v213, v95, v21 op_sel_hi:[0,1,0]
	v_mul_f32_e32 v33, v206, v21
	v_mul_f32_e32 v19, v33, v33
	v_fma_f32 v23, v201, v23, 1.0
	v_mul_f32_e32 v31, v21, v23
	v_mul_f32_e32 v21, v30, v31
	v_mov_b32_dpp v19, v19 quad_perm:[1,0,3,2] row_mask:0xf bank_mask:0xf bound_ctrl:1
	v_fmac_f32_e32 v19, v33, v33
	v_mul_f32_e32 v23, v200, v21
	v_add_f32_dpp v19, v19, v19 quad_perm:[2,3,0,1] row_mask:0xf bank_mask:0xf bound_ctrl:1
	s_nop 0
	v_mov_b32_dpp v23, v23 quad_perm:[1,0,3,2] row_mask:0xf bank_mask:0xf bound_ctrl:1
	v_fmac_f32_e32 v23, v200, v21
	v_add_f32_dpp v19, v19, v19 row_half_mirror row_mask:0xf bank_mask:0xf bound_ctrl:1
	s_nop 0
	v_add_f32_dpp v21, v23, v23 quad_perm:[2,3,0,1] row_mask:0xf bank_mask:0xf bound_ctrl:1
	v_add_f32_dpp v19, v19, v19 row_mirror row_mask:0xf bank_mask:0xf bound_ctrl:1
	ds_swizzle_b32 v22, v19 offset:swizzle(SWAP,16)
	v_add_f32_dpp v21, v21, v21 row_half_mirror row_mask:0xf bank_mask:0xf bound_ctrl:1
	s_waitcnt lgkmcnt(0)
	v_add_f32_e32 v78, v19, v22
	v_add_f32_dpp v21, v21, v21 row_mirror row_mask:0xf bank_mask:0xf bound_ctrl:1
	ds_swizzle_b32 v23, v21 offset:swizzle(SWAP,16)
	v_mov_b32_e32 v151, v78
	s_nop 1
	v_permlane32_swap_b32_e32 v78, v151
	s_waitcnt lgkmcnt(0)
	v_add_f32_e32 v19, v21, v23
	v_mov_b32_e32 v21, v19
	s_nop 1
	v_permlane32_swap_b32_e32 v19, v21
	s_and_saveexec_b64 s[12:13], vcc
	s_cbranch_execz .LBB0_2337
	v_add_f32_e32 v19, v19, v21
	v_add_u32_e32 v21, s11, v86
	v_xad_u32 v22, v21, -1, s7
	v_cndmask_b32_e64 v22, v22, v21, s[38:39]
	v_ashrrev_i32_e32 v23, 31, v22
	v_lshl_add_u64 v[22:23], s[0:1], 0, v[22:23]
	v_lshlrev_b64 v[22:23], 5, v[22:23]
	v_lshl_add_u64 v[22:23], s[8:9], 0, v[22:23]
	global_store_dword v[22:23], v19, off

; DI float sigmoidf_(float x) { return __builtin_amdgcn_rcpf(1.f + __expf(-x)); }
; DI void scan_chain_c(const P& p, int l, int chain, char* smem, const XcdBarrier* xb, const int* hint, int nhs) {
;     ...
;       const float wr = w0 + raw[tt * 64 + lane], ar = a0 + raw[2048 + tt * 64 + lane];
;       const float z = -wr;
;       const float sp = fmaxf(z, 0.f) + __logf(1.f + __expf(-fabsf(z)));
;       const float lgw = -__expf(-sp - 0.5f);
;       const float aa = sigmoidf_(ar);
;       const float kkr = kx * kkc;
;       const float kkn = kkr * __builtin_amdgcn_rsqf(fmaxf(wave_sum(kkr * kkr), 1e-24f));
;       const float km = kx * (1.f + (aa - 1.f) * kac);
;       const float bon = wave_sum(rr * km * rkc);
;       if (lane == 0) bs[((size_t)d * TA + row) * 8 + h] = bon;
;       run += lgw;
;       lw[e] = lgw; cl[e] = run; kkv[e] = kkn; bbv[e] = kkn * aa; kmv[e] = km; rrv[e] = rr; vvv[e] = vv;
;     }
;     tot[w * 64 + lane] = run;
;     __syncthreads();
;     {
;       const float t0 = tot[lane], t1 = tot[64 + lane], t2 = tot[128 + lane], t3 = tot[192 + lane];
;       const float total = t0 + t1 + t2 + t3;
;       const float prefix = (w > 0 ? t0 : 0.f) + (w > 1 ? t1 : 0.f) + (w > 2 ? t2 : 0.f);
;       if (w == 0) GL[lane] = __expf(total);
.LBB0_2351:
	s_or_b64 exec, exec, s[12:13]
	v_add_f32_e32 v26, v25, v27
	s_mov_b32 s13, 0xbfb8aa3b
	v_mul_f32_e64 v27, |v26|, s13
	v_exp_f32_e32 v27, v27
	s_mov_b32 s12, 0x800000
	v_add_f32_e32 v200, v25, v209
	s_mov_b32 s14, 0x3f317217
	v_add_f32_e32 v27, 1.0, v27
	v_cmp_gt_f32_e32 vcc, s12, v27
	v_mov_b32_e32 v218, 0x41b17218
	s_mov_b32 s15, 0x7f800000
	v_cndmask_b32_e64 v202, 0, 32, vcc
	v_ldexp_f32 v27, v27, v202
	v_log_f32_e32 v27, v27
	v_mul_f32_e64 v202, |v200|, s13
	v_exp_f32_e32 v202, v202
	v_cndmask_b32_e32 v209, 0, v218, vcc
	v_mul_f32_e32 v215, 0x3f317217, v27
	v_fma_f32 v215, v27, s14, -v215
	v_fmac_f32_e32 v215, 0x3377d1cf, v27
	v_fmac_f32_e32 v215, 0x3f317217, v27
	v_cmp_lt_f32_e64 vcc, |v27|, s15
	v_max_f32_e64 v26, -v26, 0
	s_mov_b32 s64, 0x800000
	v_cndmask_b32_e32 v27, v27, v215, vcc
	v_sub_f32_e32 v27, v27, v209
	v_add_f32_e32 v26, v26, v27
	v_add_f32_e32 v27, 1.0, v202
	v_cmp_gt_f32_e32 vcc, s12, v27
	v_sub_f32_e32 v26, -0.5, v26
	v_mul_f32_e32 v26, 0x3fb8aa3b, v26
	v_cndmask_b32_e64 v202, 0, 32, vcc
	v_ldexp_f32 v27, v27, v202
	v_log_f32_e32 v27, v27
	v_exp_f32_e32 v215, v26
	v_max_f32_e64 v26, -v200, 0
	v_add_f32_e32 v209, v25, v240
	v_mul_f32_e32 v200, 0x3f317217, v27
	v_fma_f32 v200, v27, s14, -v200
	v_fmac_f32_e32 v200, 0x3377d1cf, v27
	v_fmac_f32_e32 v200, 0x3f317217, v27
	v_cmp_lt_f32_e64 s[0:1], |v27|, s15
	v_mul_f32_e64 v216, |v209|, s13
	v_exp_f32_e32 v216, v216
	v_cndmask_b32_e64 v27, v27, v200, s[0:1]
	v_cndmask_b32_e32 v200, 0, v218, vcc
	v_sub_f32_e32 v27, v27, v200
	v_add_f32_e32 v26, v26, v27
	v_add_f32_e32 v27, v25, v210
	v_mul_f32_e64 v200, |v27|, s13
	v_exp_f32_e32 v202, v200
	v_sub_f32_e32 v26, -0.5, v26
	v_mul_f32_e32 v26, 0x3fb8aa3b, v26
	v_exp_f32_e32 v200, v26
	v_add_f32_e32 v26, 1.0, v202
	v_cmp_gt_f32_e32 vcc, s12, v26
	v_max_f32_e64 v27, -v27, 0
	v_sub_f32_e64 v210, -v215, v200
	v_cndmask_b32_e64 v202, 0, 32, vcc
	v_ldexp_f32 v26, v26, v202
	v_log_f32_e32 v26, v26
	s_nop 0
	v_mul_f32_e32 v202, 0x3f317217, v26
	v_fma_f32 v202, v26, s14, -v202
	v_fmac_f32_e32 v202, 0x3377d1cf, v26
	v_fmac_f32_e32 v202, 0x3f317217, v26
	v_cmp_lt_f32_e64 s[0:1], |v26|, s15
	s_nop 1
	v_cndmask_b32_e64 v26, v26, v202, s[0:1]
	v_cndmask_b32_e32 v202, 0, v218, vcc
	v_sub_f32_e32 v26, v26, v202
	v_add_f32_e32 v26, v27, v26
	v_add_f32_e32 v27, 1.0, v216
	v_cmp_gt_f32_e32 vcc, s12, v27
	v_sub_f32_e32 v26, -0.5, v26
	v_mul_f32_e32 v26, 0x3fb8aa3b, v26
	v_cndmask_b32_e64 v202, 0, 32, vcc
	v_ldexp_f32 v27, v27, v202
	v_log_f32_e32 v27, v27
	v_exp_f32_e32 v248, v26
	v_max_f32_e64 v26, -v209, 0
	v_add_f32_e32 v216, v25, v246
	v_mul_f32_e32 v202, 0x3f317217, v27
	v_fma_f32 v202, v27, s14, -v202
	v_fmac_f32_e32 v202, 0x3377d1cf, v27
	v_fmac_f32_e32 v202, 0x3f317217, v27
	v_cmp_lt_f32_e64 s[0:1], |v27|, s15
	v_mul_f32_e64 v217, |v216|, s13
	v_exp_f32_e32 v217, v217
	v_cndmask_b32_e64 v27, v27, v202, s[0:1]
	v_cndmask_b32_e32 v202, 0, v218, vcc
	v_sub_f32_e32 v27, v27, v202
	v_add_f32_e32 v26, v26, v27
	v_add_f32_e32 v27, v25, v243
	v_mul_f32_e64 v202, |v27|, s13
	v_exp_f32_e32 v202, v202
	v_sub_f32_e32 v26, -0.5, v26
	v_mul_f32_e32 v26, 0x3fb8aa3b, v26
	v_exp_f32_e32 v209, v26
	v_add_f32_e32 v26, 1.0, v202
	v_cmp_gt_f32_e32 vcc, s12, v26
	v_max_f32_e64 v27, -v27, 0
	v_sub_f32_e32 v219, v210, v248
	v_cndmask_b32_e64 v202, 0, 32, vcc
	v_ldexp_f32 v26, v26, v202
	v_log_f32_e32 v26, v26
	v_sub_f32_e32 v240, v219, v209
	v_mul_f32_e32 v202, 0x3f317217, v26
	v_fma_f32 v202, v26, s14, -v202
	v_fmac_f32_e32 v202, 0x3377d1cf, v26
	v_fmac_f32_e32 v202, 0x3f317217, v26
	v_cmp_lt_f32_e64 s[0:1], |v26|, s15
	s_nop 1
	v_cndmask_b32_e64 v26, v26, v202, s[0:1]
	v_cndmask_b32_e32 v202, 0, v218, vcc
	v_sub_f32_e32 v26, v26, v202
	v_add_f32_e32 v26, v27, v26
	v_add_f32_e32 v27, 1.0, v217
	v_cmp_gt_f32_e32 vcc, s12, v27
	v_sub_f32_e32 v26, -0.5, v26
	v_mul_f32_e32 v26, 0x3fb8aa3b, v26
	v_cndmask_b32_e64 v202, 0, 32, vcc
	v_ldexp_f32 v27, v27, v202
	v_log_f32_e32 v27, v27
	v_exp_f32_e32 v249, v26
	v_max_f32_e64 v26, -v216, 0
	v_add_f32_e32 v216, v25, v247
	v_mul_f32_e32 v202, 0x3f317217, v27
	v_fma_f32 v202, v27, s14, -v202
	v_mul_f32_e64 v217, |v216|, s13
	v_fmac_f32_e32 v202, 0x3377d1cf, v27
	v_exp_f32_e32 v217, v217
	v_fmac_f32_e32 v202, 0x3f317217, v27
	v_cmp_lt_f32_e64 s[0:1], |v27|, s15
	v_add_f32_e32 v25, v25, v208
	v_mul_f32_e64 v208, |v25|, s13
	v_cndmask_b32_e64 v27, v27, v202, s[0:1]
	v_cndmask_b32_e32 v202, 0, v218, vcc
	v_sub_f32_e32 v27, v27, v202
	v_add_f32_e32 v26, v26, v27
	v_add_f32_e32 v27, 1.0, v217
	v_cmp_gt_f32_e32 vcc, s12, v27
	v_exp_f32_e32 v208, v208
	v_sub_f32_e32 v26, -0.5, v26
	v_cndmask_b32_e64 v202, 0, 32, vcc
	v_ldexp_f32 v27, v27, v202
	v_log_f32_e32 v27, v27
	v_mul_f32_e32 v26, 0x3fb8aa3b, v26
	v_exp_f32_e32 v243, v26
	v_max_f32_e64 v26, -v216, 0
	v_mul_f32_e32 v202, 0x3f317217, v27
	v_fma_f32 v202, v27, s14, -v202
	v_fmac_f32_e32 v202, 0x3377d1cf, v27
	v_fmac_f32_e32 v202, 0x3f317217, v27
	v_cmp_lt_f32_e64 s[0:1], |v27|, s15
	v_max_f32_e64 v25, -v25, 0
	v_sub_f32_e32 v227, v240, v249
	v_cndmask_b32_e64 v27, v27, v202, s[0:1]
	v_cndmask_b32_e32 v202, 0, v218, vcc
	v_sub_f32_e32 v27, v27, v202
	v_add_f32_e32 v26, v26, v27
	v_add_f32_e32 v27, 1.0, v208
	v_cmp_gt_f32_e32 vcc, s12, v27
	v_sub_f32_e32 v26, -0.5, v26
	v_mul_f32_e32 v26, 0x3fb8aa3b, v26
	v_cndmask_b32_e64 v202, 0, 32, vcc
	v_ldexp_f32 v27, v27, v202
	v_log_f32_e32 v27, v27
	v_exp_f32_e32 v250, v26
	v_sub_f32_e32 v226, v227, v243
	v_mul_f32_e32 v26, 0x3f317217, v27
	v_fma_f32 v26, v27, s14, -v26
	v_fmac_f32_e32 v26, 0x3377d1cf, v27
	v_fmac_f32_e32 v26, 0x3f317217, v27
	v_cmp_lt_f32_e64 s[0:1], |v27|, s15
	v_sub_f32_e32 v251, v226, v250
	s_nop 0
	v_cndmask_b32_e64 v26, v27, v26, s[0:1]
	v_cndmask_b32_e32 v27, 0, v218, vcc
	v_sub_f32_e32 v26, v26, v27
	v_add_f32_e32 v25, v25, v26
	v_sub_f32_e32 v25, -0.5, v25
	v_mul_f32_e32 v25, 0x3fb8aa3b, v25
	v_exp_f32_e32 v208, v25
	v_lshl_add_u32 v25, v80, 2, v113
	v_sub_f32_e32 v246, v251, v208
	ds_write_b32 v25, v246 offset:16384
	s_waitcnt lgkmcnt(0)
	s_barrier
	ds_read2st64_b32 v[26:27], v24 offset0:64 offset1:65
	ds_read2st64_b32 v[24:25], v24 offset0:66 offset1:67
	s_waitcnt lgkmcnt(1)
	v_add_f32_e32 v202, v26, v27
	s_waitcnt lgkmcnt(0)
	v_add_f32_e32 v202, v202, v24
	v_add_f32_e32 v247, v202, v25
	s_and_saveexec_b64 s[0:1], s[48:49]
	s_cbranch_execz .LBB0_2353
	v_mul_f32_e32 v25, 0x3fb8aa3b, v247
	v_exp_f32_e32 v25, v25
	v_mov_b32_e32 v202, 0x11c00
	v_lshl_add_u32 v202, v80, 2, v202
	ds_write_b32 v202, v25
; DI float sigmoidf_(float x) { return __builtin_amdgcn_rcpf(1.f + __expf(-x)); }
; DI void scan_chain_c(const P& p, int l, int chain, char* smem, const XcdBarrier* xb, const int* hint, int nhs) {
;     ...
;       const float rr = trA * (float)xr[e] + tr1 * (float)xr[e + 1] + trC * (float)xr[e + 2];
;       const float kx = tkA * (float)xk[e] + tk1 * (float)xk[e + 1] + tkC * (float)xk[e + 2];
;       const float vv = tvA * (float)xv[e] + tv1 * (float)xv[e + 1] + tvC * (float)xv[e + 2];
;       const float wr = w0 + raw[tt * 64 + lane], ar = a0 + raw[2048 + tt * 64 + lane];
;       const float z = -wr;
;       const float sp = fmaxf(z, 0.f) + __logf(1.f + __expf(-fabsf(z)));
;       const float lgw = -__expf(-sp - 0.5f);
;       const float aa = sigmoidf_(ar);
;       const float kkr = kx * kkc;
;       const float kkn = kkr * __builtin_amdgcn_rsqf(fmaxf(wave_sum(kkr * kkr), 1e-24f));
;       const float km = kx * (1.f + (aa - 1.f) * kac);
;       const float bon = wave_sum(rr * km * rkc);
;       if (lane == 0) bs[((size_t)d * TA + row) * 8 + h] = bon;
;       run += lgw;
;       lw[e] = lgw; cl[e] = run; kkv[e] = kkn; bbv[e] = kkn * aa; kmv[e] = km; rrv[e] = rr; vvv[e] = vv;
;     }
;     tot[w * 64 + lane] = run;
;     __syncthreads();
;     {
;       const float t0 = tot[lane], t1 = tot[64 + lane], t2 = tot[128 + lane], t3 = tot[192 + lane];
;       const float total = t0 + t1 + t2 + t3;
;       const float prefix = (w > 0 ? t0 : 0.f) + (w > 1 ? t1 : 0.f) + (w > 2 ? t2 : 0.f);
;       if (w == 0) GL[lane] = __expf(total);
;       b16x8 bgv, kgv, vtv;
; #pragma unroll
;       for (int e = 0; e < 8; ++e) {
;         const int tt = 8 * w + e;
;         const float g = prefix + cl[e];
;         const float eg = __expf(g), ege = __expf(g - lw[e]);
;         const float eng = __builtin_amdgcn_rcpf(eg);
;         const float egl = __expf(total - g);
;         Qt[tt * 72 + lane] = (b16)(kkv[e] * ege);
;         Rt[tt * 72 + lane] = (b16)(rrv[e] * eg);
;         Bt[tt * 72 + lane] = (b16)(bbv[e] * eng);
;         Kt[tt * 72 + lane] = (b16)(kmv[e] * eng);
;         bgv[e] = (b16)(bbv[e] * egl);
;         kgv[e] = (b16)(kmv[e] * egl);
;         vtv[e] = (b16)vvv[e];
.LBB0_2353:
	s_or_b64 exec, exec, s[0:1]
	v_add_f32_e32 v25, v213, v214
	v_max_f32_e32 v25, 0x179abe15, v25
	v_rsq_f32_e32 v25, v25
	v_cndmask_b32_e64 v26, 0, v26, s[42:43]
	v_cndmask_b32_e64 v27, 0, v27, s[44:45]
	v_cndmask_b32_e64 v24, 0, v24, s[46:47]
	v_mul_f32_e32 v206, v206, v25
	v_add_f32_e32 v25, v26, v27
	v_add_f32_e32 v26, v244, v245
	v_max_f32_e32 v26, 0x179abe15, v26
	v_rsq_f32_e32 v26, v26
	v_cvt_f32_f16_e32 v27, v111
	v_add_f32_e32 v213, v25, v24
	v_cvt_f32_f16_e32 v24, v123
	v_mul_f32_e32 v214, v242, v26
	v_add_f32_e32 v26, v238, v239
	v_max_f32_e32 v26, 0x179abe15, v26
	v_rsq_f32_e32 v26, v26
	v_cvt_f32_f16_e32 v217, v108
	v_mul_f32_e32 v24, v28, v24
	v_fma_mix_f32 v24, v0, v111, v24 op_sel_hi:[0,1,0]
	v_mul_f32_e32 v212, v212, v26
	v_mul_f32_e32 v26, v28, v27
	v_add_f32_e32 v27, v204, v205
	v_max_f32_e32 v27, 0x179abe15, v27
	v_rsq_f32_e32 v27, v27
	v_fma_mix_f32 v26, v0, v108, v26 op_sel_hi:[0,1,0]
	s_waitcnt vmcnt(0)
	v_fma_mix_f32 v204, v29, v123, v26 op_sel_hi:[0,1,0]
	v_cvt_f32_f16_e32 v26, v104
	v_mul_f32_e32 v205, v199, v27
	v_mul_f32_e32 v27, v28, v217
	v_fma_mix_f32 v27, v0, v104, v27 op_sel_hi:[0,1,0]
	v_add_f32_e32 v183, v183, v184
	v_fma_mix_f32 v216, v29, v147, v24 op_sel_hi:[0,1,0]
	v_mul_f32_e32 v24, v211, v212
	v_add_f32_e32 v195, v195, v196
	v_fma_mix_f32 v196, v29, v111, v27 op_sel_hi:[0,1,0]
	v_cvt_f32_f16_e32 v211, v102
	v_add_f32_e32 v27, v189, v190
	v_max_f32_e32 v183, 0x179abe15, v183
	v_max_f32_e32 v27, 0x179abe15, v27
	v_rsq_f32_e32 v183, v183
	v_mul_f32_e32 v26, v28, v26
	v_rsq_f32_e32 v27, v27
	v_cvt_f32_f16_e32 v190, v98
	v_fma_mix_f32 v26, v0, v102, v26 op_sel_hi:[0,1,0]
	v_fma_mix_f32 v189, v29, v108, v26 op_sel_hi:[0,1,0]
	v_mul_f32_e32 v26, v28, v211
	v_fma_mix_f32 v26, v0, v98, v26 op_sel_hi:[0,1,0]
	v_mul_f32_e32 v182, v182, v183
	v_add_f32_e32 v78, v78, v151
	v_mul_f32_e32 v188, v188, v27
	v_fma_mix_f32 v184, v29, v104, v26 op_sel_hi:[0,1,0]
	v_mul_f32_e32 v26, v181, v182
	v_mul_f32_e32 v181, v28, v190
	v_max_f32_e32 v78, 0x179abe15, v78
	v_mul_f32_e32 v27, v186, v188
	v_cvt_f32_f16_e32 v186, v96
	v_rsq_f32_e32 v78, v78
	v_fma_mix_f32 v151, v0, v96, v181 op_sel_hi:[0,1,0]
	v_cvt_f32_f16_e32 v181, v92
	v_sub_f32_e32 v202, 0, v215
	v_mul_f32_e32 v33, v33, v78
	v_mul_f32_e32 v78, v28, v186
	v_mul_f32_e32 v28, v28, v181
	v_fma_mix_f32 v78, v0, v92, v78 op_sel_hi:[0,1,0]
	v_fma_mix_f32 v0, v0, v90, v28 op_sel_hi:[0,1,0]
	v_add_f32_e32 v28, v202, v213
	v_fma_mix_f32 v151, v29, v102, v151 op_sel_hi:[0,1,0]
	v_fma_mix_f32 v78, v29, v98, v78 op_sel_hi:[0,1,0]
	v_fma_mix_f32 v0, v29, v96, v0 op_sel_hi:[0,1,0]
	v_mul_f32_e32 v29, 0x3fb8aa3b, v28
	v_exp_f32_e32 v29, v29
	v_add_f32_e32 v181, v215, v28
	v_mul_f32_e32 v181, 0x3fb8aa3b, v181
	v_exp_f32_e32 v181, v181
	v_rcp_f32_e32 v183, v29
	v_sub_f32_e32 v28, v247, v28
	v_mul_f32_e32 v29, v30, v29
	v_mul_f32_e32 v32, v32, v33
	v_mul_f32_e32 v28, 0x3fb8aa3b, v28
	v_mul_f32_e32 v33, v33, v181
	v_add_lshl_u32 v181, v80, v144, 1
	v_cvt_pk_bf16_f32 v29, v29, s0
	v_exp_f32_e32 v28, v28
	ds_write_b16 v181, v29 offset:22016
	v_mul_f32_e32 v29, v32, v183
	v_cvt_pk_bf16_f32 v29, v29, s0
	ds_write_b16 v181, v29 offset:26624
	v_mul_f32_e32 v29, v31, v183
	v_cvt_pk_bf16_f32 v29, v29, s0
	ds_write_b16 v181, v29 offset:31232
	v_mul_f32_e32 v29, v32, v28
	v_mul_f32_e32 v28, v31, v28
	v_cvt_pk_bf16_f32 v31, v28, s0
	v_add_f32_e32 v28, v210, v213
	v_cvt_pk_bf16_f32 v30, v29, s0
	v_mul_f32_e32 v29, 0x3fb8aa3b, v28
	v_exp_f32_e32 v29, v29
	v_cvt_pk_bf16_f32 v33, v33, s0
	ds_write_b16 v181, v33 offset:17408
	v_add_f32_e32 v32, v200, v28
	v_rcp_f32_e32 v33, v29
	v_mul_f32_e32 v32, 0x3fb8aa3b, v32
	v_mul_f32_e32 v29, v76, v29
	v_exp_f32_e32 v32, v32
	v_cvt_pk_bf16_f32 v29, v29, s0
	ds_write_b16 v181, v29 offset:22160
	v_mul_f32_e32 v29, v26, v33
	v_cvt_pk_bf16_f32 v29, v29, s0
	ds_write_b16 v181, v29 offset:26768
	v_mul_f32_e32 v29, v18, v33
	v_mul_f32_e32 v32, v182, v32
	v_cvt_pk_bf16_f32 v29, v29, s0
	v_cvt_pk_bf16_f32 v32, v32, s0
	ds_write_b16 v181, v29 offset:31376
	v_add_f32_e32 v29, v219, v213
	ds_write_b16 v181, v32 offset:17552
	v_mul_f32_e32 v32, 0x3fb8aa3b, v29
	v_exp_f32_e32 v32, v32
	v_sub_f32_e32 v28, v247, v28
	v_add_f32_e32 v33, v248, v29
	v_sub_f32_e32 v29, v247, v29
	v_rcp_f32_e32 v76, v32
	v_mul_f32_e32 v28, 0x3fb8aa3b, v28
	v_mul_f32_e32 v29, 0x3fb8aa3b, v29
	v_exp_f32_e32 v28, v28
	v_exp_f32_e32 v29, v29
	v_mul_f32_e32 v32, v180, v32
	v_cvt_pk_bf16_f32 v32, v32, s0
	ds_write_b16 v181, v32 offset:22304
	v_mul_f32_e32 v32, v27, v76
	v_mul_f32_e32 v33, 0x3fb8aa3b, v33
	v_cvt_pk_bf16_f32 v32, v32, s0
	v_exp_f32_e32 v33, v33
	ds_write_b16 v181, v32 offset:26912
	v_mul_f32_e32 v32, v19, v76
	v_pk_mul_f32 v[26:27], v[26:27], v[28:29]
	v_pk_mul_f32 v[18:19], v[18:19], v[28:29]
	v_add_f32_e32 v28, v240, v213
	v_mul_f32_e32 v29, 0x3fb8aa3b, v28
	v_exp_f32_e32 v29, v29
	v_max_f32_e32 v195, 0x179abe15, v195
	v_rsq_f32_e32 v195, v195
	v_mul_f32_e32 v33, v188, v33
	v_cvt_pk_bf16_f32 v33, v33, s0
	v_cvt_pk_bf16_f32 v32, v32, s0
	s_mov_b32 s0, 0x5040100
	v_cvt_pk_bf16_f32 v19, v18, v19
	v_cvt_pk_bf16_f32 v27, v26, v27
	v_perm_b32 v18, v19, v31, s0
	v_rcp_f32_e32 v31, v29
	v_perm_b32 v26, v27, v30, s0
	v_add_f32_e32 v30, v209, v28
	v_mul_f32_e32 v193, v193, v195
	v_mul_f32_e32 v30, 0x3fb8aa3b, v30
	v_mul_f32_e32 v29, v185, v29
	v_mul_f32_e32 v199, v198, v205
	v_mul_f32_e32 v198, v192, v193
	v_exp_f32_e32 v30, v30
	v_cvt_pk_bf16_f32 v29, v29, s0
	ds_write_b16 v181, v29 offset:22448
	v_mul_f32_e32 v29, v198, v31
	v_cvt_pk_bf16_f32 v29, v29, s0
	ds_write_b16 v181, v29 offset:27056
	v_mul_f32_e32 v29, v20, v31
	v_mul_f32_e32 v30, v193, v30
	v_cvt_pk_bf16_f32 v29, v29, s0
; DI void scan_chain_c(const P& p, int l, int chain, char* smem, const XcdBarrier* xb, const int* hint, int nhs) {
;     ...
;       b16x8 bgv, kgv, vtv;
; #pragma unroll
;       for (int e = 0; e < 8; ++e) {
;         const int tt = 8 * w + e;
;         const float g = prefix + cl[e];
;         const float eg = __expf(g), ege = __expf(g - lw[e]);
;         const float eng = __builtin_amdgcn_rcpf(eg);
;         const float egl = __expf(total - g);
;         Qt[tt * 72 + lane] = (b16)(kkv[e] * ege);
;         Rt[tt * 72 + lane] = (b16)(rrv[e] * eg);
;         Bt[tt * 72 + lane] = (b16)(bbv[e] * eng);
;         Kt[tt * 72 + lane] = (b16)(kmv[e] * eng);
;         bgv[e] = (b16)(bbv[e] * egl);
;         kgv[e] = (b16)(kmv[e] * egl);
;         vtv[e] = (b16)vvv[e];
;       }
;       *(b16x8*)(BgT + lane * 40 + 8 * w) = bgv;
;       *(b16x8*)(KgT + lane * 40 + 8 * w) = kgv;
;       *(b16x8*)(VT + lane * 40 + 8 * w) = vtv;
;     }
;     __syncthreads();
	v_cvt_pk_bf16_f32 v30, v30, s0
	ds_write_b16 v181, v29 offset:31664
	v_add_f32_e32 v29, v227, v213
	ds_write_b16 v181, v30 offset:17840
	v_mul_f32_e32 v30, 0x3fb8aa3b, v29
	v_exp_f32_e32 v30, v30
	ds_write_b16 v181, v32 offset:31520
	v_add_f32_e32 v31, v249, v29
	v_sub_f32_e32 v28, v247, v28
	v_rcp_f32_e32 v32, v30
	v_mul_f32_e32 v31, 0x3fb8aa3b, v31
	v_sub_f32_e32 v29, v247, v29
	v_mul_f32_e32 v28, 0x3fb8aa3b, v28
	v_exp_f32_e32 v31, v31
	v_mul_f32_e32 v29, 0x3fb8aa3b, v29
	v_mul_f32_e32 v30, v187, v30
	v_exp_f32_e32 v28, v28
	v_exp_f32_e32 v29, v29
	v_cvt_pk_bf16_f32 v30, v30, s0
	ds_write_b16 v181, v30 offset:22592
	v_mul_f32_e32 v30, v199, v32
	v_cvt_pk_bf16_f32 v30, v30, s0
	v_mul_f32_e32 v31, v205, v31
	ds_write_b16 v181, v30 offset:27200
	v_mul_f32_e32 v30, v21, v32
	v_cvt_pk_bf16_f32 v31, v31, s0
	v_cvt_pk_bf16_f32 v30, v30, s0
	v_pk_mul_f32 v[20:21], v[20:21], v[28:29]
	ds_write_b16 v181, v31 offset:17984
	ds_write_b16 v181, v30 offset:31808
	v_pk_mul_f32 v[30:31], v[198:199], v[28:29]
	v_cvt_pk_bf16_f32 v29, v20, v21
	v_add_f32_e32 v20, v226, v213
	v_mul_f32_e32 v21, 0x3fb8aa3b, v20
	v_exp_f32_e32 v21, v21
	v_cvt_pk_bf16_f32 v30, v30, v31
	v_add_f32_e32 v28, v243, v20
	v_mul_f32_e32 v28, 0x3fb8aa3b, v28
	v_rcp_f32_e32 v31, v21
	v_mul_f32_e32 v21, v191, v21
	v_exp_f32_e32 v28, v28
	v_cvt_pk_bf16_f32 v21, v21, s0
	ds_write_b16 v181, v21 offset:22736
	v_mul_f32_e32 v21, v24, v31
	v_cvt_pk_bf16_f32 v21, v21, s0
	ds_write_b16 v181, v21 offset:27344
	v_mul_f32_e32 v21, v22, v31
	v_mul_f32_e32 v28, v212, v28
	v_cvt_pk_bf16_f32 v21, v21, s0
	v_cvt_pk_bf16_f32 v28, v28, s0
	ds_write_b16 v181, v21 offset:31952
	v_add_f32_e32 v21, v251, v213
	ds_write_b16 v181, v28 offset:18128
	v_mul_f32_e32 v28, 0x3fb8aa3b, v21
	v_exp_f32_e32 v28, v28
	v_sub_f32_e32 v20, v247, v20
	v_add_f32_e32 v31, v250, v21
	v_sub_f32_e32 v21, v247, v21
	v_mul_f32_e32 v20, 0x3fb8aa3b, v20
	v_rcp_f32_e32 v32, v28
	v_mul_f32_e32 v21, 0x3fb8aa3b, v21
	v_exp_f32_e32 v20, v20
	v_exp_f32_e32 v21, v21
	v_mul_f32_e32 v28, v194, v28
	v_mul_f32_e32 v25, v241, v214
	v_cvt_pk_bf16_f32 v28, v28, s0
	ds_write_b16 v181, v28 offset:22880
	v_mul_f32_e32 v28, v25, v32
	v_cvt_pk_bf16_f32 v28, v28, s0
	v_pk_mul_f32 v[24:25], v[24:25], v[20:21]
	v_pk_mul_f32 v[20:21], v[22:23], v[20:21]
	v_add_f32_e32 v22, v246, v213
	ds_write_b16 v181, v28 offset:27488
	v_mul_f32_e32 v28, v23, v32
	v_mul_f32_e32 v23, 0x3fb8aa3b, v22
	v_exp_f32_e32 v23, v23
	v_cvt_pk_bf16_f32 v21, v20, v21
	v_alignbit_b32 v19, v29, v19, 16
	v_alignbit_b32 v20, v21, v29, 16
	v_rcp_f32_e32 v29, v23
	v_cvt_pk_bf16_f32 v24, v24, v25
	v_add_f32_e32 v25, v208, v22
	v_sub_f32_e32 v22, v247, v22
	v_mul_f32_e32 v23, v197, v23
	v_mul_f32_e32 v207, v207, v206
	v_mul_f32_e32 v31, 0x3fb8aa3b, v31
	v_mul_f32_e32 v22, 0x3fb8aa3b, v22
	v_cvt_pk_bf16_f32 v23, v23, s0
	v_exp_f32_e32 v31, v31
	v_mul_f32_e32 v25, 0x3fb8aa3b, v25
	v_exp_f32_e32 v22, v22
	ds_write_b16 v181, v23 offset:23024
	v_mul_f32_e32 v23, v207, v29
	v_exp_f32_e32 v25, v25
	v_cvt_pk_bf16_f32 v23, v23, s0
	ds_write_b16 v181, v23 offset:27632
	v_mul_f32_e32 v23, v201, v29
	v_cvt_pk_bf16_f32 v23, v23, s0
	v_mul_f32_e32 v31, v214, v31
	ds_write_b16 v181, v23 offset:32240
	v_mul_f32_e32 v23, v207, v22
	v_mul_f32_e32 v22, v201, v22
	v_cvt_pk_bf16_f32 v31, v31, s0
	v_cvt_pk_bf16_f32 v28, v28, s0
	v_mul_f32_e32 v25, v206, v25
	v_cvt_pk_bf16_f32 v23, v23, s0
	v_cvt_pk_bf16_f32 v22, v22, s0
	v_alignbit_b32 v27, v30, v27, 16
	ds_write_b16 v181, v31 offset:18272
	ds_write_b16 v181, v28 offset:32096
	v_alignbit_b32 v28, v24, v30, 16
	v_cvt_pk_bf16_f32 v25, v25, s0
	v_alignbit_b32 v29, v23, v24, 16
	v_alignbit_b32 v21, v22, v21, 16
	v_cvt_pk_bf16_f32 v22, v0, v78
	v_mad_u64_u32 v[30:31], s[0:1], v80, s76, v[66:67]
	v_mul_u32_u24_e32 v0, 0x48, v148
	ds_write_b16 v181, v33 offset:17696
	ds_write_b16 v181, v25 offset:18416
	v_cvt_pk_bf16_f32 v25, v204, v216
	v_cvt_pk_bf16_f32 v24, v189, v196
	v_cvt_pk_bf16_f32 v23, v151, v184
	ds_write_b128 v30, v[26:29] offset:35840
	ds_write_b128 v30, v[18:21] offset:40960
	ds_write_b128 v30, v[22:25] offset:46080
	v_lshlrev_b32_e32 v0, 1, v0
	v_lshlrev_b32_e32 v22, 4, v150
	v_add3_u32 v76, v114, v0, v22
	s_waitcnt lgkmcnt(0)
	s_barrier
; #define MFMAB(a, b, c) __builtin_amdgcn_mfma_f32_32x32x16_bf16((a), (b), (c), 0, 0, 0)
; DI void scan_chain_c(const P& p, int l, int chain, char* smem, const XcdBarrier* xb, const int* hint, int nhs) {
;     ...
;     {
;       const b16* X = (w < 2) ? Qt : Rt;
;       const b16* Y = (w & 1) ? Kt : Bt;
;       f32x16 acc;
; #pragma unroll
;       for (int i = 0; i < 16; ++i) acc[i] = 0.f;
; #pragma unroll
;       for (int ks = 0; ks < 4; ++ks) {
;         b16x8 a = *(const b16x8*)(X + r * 72 + ks * 16 + 8 * hh);
;         b16x8 bb = *(const b16x8*)(Y + r * 72 + ks * 16 + 8 * hh);
;         acc = MFMAB(a, bb, acc);
;       }
; #pragma unroll
;       for (int i = 0; i < 16; ++i) {
;         const int t = 4 * hh + (i & 3) + 8 * (i >> 2);
;         const bool keep = (w < 2) ? (r < t) : (r <= t);
;         const float v = keep ? acc[i] : 0.f;
;         if (w == 0) Am[t * 36 + r] = v;
;         else if (w == 1) Bm[t * 40 + r] = (b16)v;
;         else if (w == 2) A2[t * 40 + r] = (b16)v;
;         else B2[t * 40 + r] = (b16)v;
;       }
	ds_read_b128 v[18:21], v76
	v_add3_u32 v0, v115, v0, v22
	ds_read_b128 v[22:25], v0
	s_waitcnt lgkmcnt(0)
	v_mfma_f32_32x32x16_bf16 v[18:33], v[18:21], v[22:25], 0
	ds_read_b128 v[180:183], v76 offset:32
	ds_read_b128 v[184:187], v0 offset:32
	v_cmp_lt_i32_e32 vcc, v148, v77
	v_lshlrev_b32_e32 v151, 3, v150
	s_mov_b64 s[0:1], 0
	v_cndmask_b32_e64 v78, 0, 1, vcc
	v_cmp_le_i32_e32 vcc, v148, v77
	s_mov_b64 s[14:15], 0
	s_waitcnt lgkmcnt(0)
	v_mfma_f32_32x32x16_bf16 v[18:33], v[180:183], v[184:187], v[18:33]
	ds_read_b128 v[180:183], v76 offset:64
	ds_read_b128 v[184:187], v0 offset:64
	s_waitcnt lgkmcnt(0)
	v_mfma_f32_32x32x16_bf16 v[18:33], v[180:183], v[184:187], v[18:33]
	ds_read_b128 v[180:183], v76 offset:96
	ds_read_b128 v[184:187], v0 offset:96
	v_lshlrev_b32_e32 v76, 1, v148
	v_or_b32_e32 v0, 0x10800, v76
	s_waitcnt lgkmcnt(0)
	v_mfma_f32_32x32x16_bf16 v[18:33], v[180:183], v[184:187], v[18:33]
	v_sub_u32_e32 v180, v148, v77
	v_cndmask_b32_e64 v181, 1, 0, s[50:51]
	v_readfirstlane_b32 s0, v67
	v_sub_u32_e32 v180, v180, v181
	v_mul_u32_u24_e32 v182, 0x140, v150
	v_mul_u32_u24_e32 v183, 0x90, v148
	s_mul_i32 s1, s0, 0xa00
	s_add_i32 s1, s1, 0xf400
	v_lshl_add_u32 v182, v148, 1, v182
	v_lshl_add_u32 v183, v150, 4, v183
	v_add_u32_e32 v182, s1, v182
	s_cmp_eq_u32 s0, 0
	s_cbranch_scc1 .Lscan_s3_w0
	v_cmp_gt_i32_e64 vcc, 0, v180
	v_cmp_gt_i32_e64 s[0:1], 1, v180
	v_cmp_gt_i32_e64 s[12:13], 2, v180
	v_cmp_gt_i32_e64 s[14:15], 3, v180
	v_cndmask_b32_e32 v184, 0, v18, vcc
	v_cndmask_b32_e64 v185, 0, v19, s[0:1]
	v_cndmask_b32_e64 v186, 0, v20, s[12:13]
	v_cndmask_b32_e64 v187, 0, v21, s[14:15]
	v_cvt_pk_bf16_f32 v184, v184, v184
	v_cvt_pk_bf16_f32 v185, v185, v185
	v_cvt_pk_bf16_f32 v186, v186, v186
	v_cvt_pk_bf16_f32 v187, v187, v187
	ds_write_b16 v182, v184 offset:0
	ds_write_b16 v182, v185 offset:80
	ds_write_b16 v182, v186 offset:160
	ds_write_b16 v182, v187 offset:240
	v_cmp_gt_i32_e64 vcc, 8, v180
	v_cmp_gt_i32_e64 s[0:1], 9, v180
	v_cmp_gt_i32_e64 s[12:13], 10, v180
	v_cmp_gt_i32_e64 s[14:15], 11, v180
	v_cndmask_b32_e32 v188, 0, v22, vcc
	v_cndmask_b32_e64 v189, 0, v23, s[0:1]
	v_cndmask_b32_e64 v190, 0, v24, s[12:13]
	v_cndmask_b32_e64 v191, 0, v25, s[14:15]
	v_cvt_pk_bf16_f32 v188, v188, v188
	v_cvt_pk_bf16_f32 v189, v189, v189
	v_cvt_pk_bf16_f32 v190, v190, v190
	v_cvt_pk_bf16_f32 v191, v191, v191
	ds_write_b16 v182, v188 offset:640
	ds_write_b16 v182, v189 offset:720
	ds_write_b16 v182, v190 offset:800
	ds_write_b16 v182, v191 offset:880
	v_cmp_gt_i32_e64 vcc, 16, v180
	v_cmp_gt_i32_e64 s[0:1], 17, v180
	v_cmp_gt_i32_e64 s[12:13], 18, v180
	v_cmp_gt_i32_e64 s[14:15], 19, v180
	v_cndmask_b32_e32 v184, 0, v26, vcc
	v_cndmask_b32_e64 v185, 0, v27, s[0:1]
	v_cndmask_b32_e64 v186, 0, v28, s[12:13]
	v_cndmask_b32_e64 v187, 0, v29, s[14:15]
	v_cvt_pk_bf16_f32 v184, v184, v184
	v_cvt_pk_bf16_f32 v185, v185, v185
	v_cvt_pk_bf16_f32 v186, v186, v186
	v_cvt_pk_bf16_f32 v187, v187, v187
	ds_write_b16 v182, v184 offset:1280
	ds_write_b16 v182, v185 offset:1360
	ds_write_b16 v182, v186 offset:1440
	ds_write_b16 v182, v187 offset:1520
	v_cmp_gt_i32_e64 vcc, 24, v180
	v_cmp_gt_i32_e64 s[0:1], 25, v180
	v_cmp_gt_i32_e64 s[12:13], 26, v180
	v_cmp_gt_i32_e64 s[14:15], 27, v180
	v_cndmask_b32_e32 v188, 0, v30, vcc
	v_cndmask_b32_e64 v189, 0, v31, s[0:1]
	v_cndmask_b32_e64 v190, 0, v32, s[12:13]
	v_cndmask_b32_e64 v191, 0, v33, s[14:15]
	v_cvt_pk_bf16_f32 v188, v188, v188
	v_cvt_pk_bf16_f32 v189, v189, v189
	v_cvt_pk_bf16_f32 v190, v190, v190
	v_cvt_pk_bf16_f32 v191, v191, v191
	ds_write_b16 v182, v188 offset:1920
	ds_write_b16 v182, v189 offset:2000
	ds_write_b16 v182, v190 offset:2080
	ds_write_b16 v182, v191 offset:2160
	s_branch .Lscan_s3_done
.Lscan_s3_w0:
	v_cmp_gt_i32_e64 vcc, 0, v180
	v_cmp_gt_i32_e64 s[0:1], 1, v180
	v_cmp_gt_i32_e64 s[12:13], 2, v180
	v_cmp_gt_i32_e64 s[14:15], 3, v180
	v_cndmask_b32_e32 v184, 0, v18, vcc
	v_cndmask_b32_e64 v185, 0, v19, s[0:1]
	v_cndmask_b32_e64 v186, 0, v20, s[12:13]
	v_cndmask_b32_e64 v187, 0, v21, s[14:15]
	ds_write_b128 v183, v[184:187] offset:60416
	v_cmp_gt_i32_e64 vcc, 8, v180
	v_cmp_gt_i32_e64 s[0:1], 9, v180
	v_cmp_gt_i32_e64 s[12:13], 10, v180
	v_cmp_gt_i32_e64 s[14:15], 11, v180
	v_cndmask_b32_e32 v188, 0, v22, vcc
	v_cndmask_b32_e64 v189, 0, v23, s[0:1]
	v_cndmask_b32_e64 v190, 0, v24, s[12:13]
	v_cndmask_b32_e64 v191, 0, v25, s[14:15]
	ds_write_b128 v183, v[188:191] offset:60448
	v_cmp_gt_i32_e64 vcc, 16, v180
	v_cmp_gt_i32_e64 s[0:1], 17, v180
	v_cmp_gt_i32_e64 s[12:13], 18, v180
	v_cmp_gt_i32_e64 s[14:15], 19, v180
	v_cndmask_b32_e32 v184, 0, v26, vcc
	v_cndmask_b32_e64 v185, 0, v27, s[0:1]
	v_cndmask_b32_e64 v186, 0, v28, s[12:13]
	v_cndmask_b32_e64 v187, 0, v29, s[14:15]
	ds_write_b128 v183, v[184:187] offset:60480
	v_cmp_gt_i32_e64 vcc, 24, v180
	v_cmp_gt_i32_e64 s[0:1], 25, v180
	v_cmp_gt_i32_e64 s[12:13], 26, v180
	v_cmp_gt_i32_e64 s[14:15], 27, v180
	v_cndmask_b32_e32 v188, 0, v30, vcc
	v_cndmask_b32_e64 v189, 0, v31, s[0:1]
	v_cndmask_b32_e64 v190, 0, v32, s[12:13]
	v_cndmask_b32_e64 v191, 0, v33, s[14:15]
	ds_write_b128 v183, v[188:191] offset:60512

; DI void scan_chain_c(const P& p, int l, int chain, char* smem, const XcdBarrier* xb, const int* hint, int nhs) {
;     ...
;     {
;       if (n0 + 32 < 256 + 4096) prefetch_af(n0 + 32);
;       const int q = lane & 3, col = 16 * w + (lane >> 2);
;       float uq[8];
; #pragma unroll
;       for (int e = 0; e < 8; ++e) uq[e] = 0.f;
;       int o0 = 0, o1 = 0;
; #pragma unroll
;       for (int t = 0; t < 32; ++t) {
;         const int oo = (t & 1) ? o1 : o0;
;         const float gt = GT[t * 64 + col + oo];
;         float ut = gt;
;         if (t > 0) {
;           const f32x4 am0 = *(const f32x4*)(Am + t * 36 + 8 * q + oo);
;           const f32x4 am1 = *(const f32x4*)(Am + t * 36 + 8 * q + 4 + oo);
;           float part = (am0.x * uq[0] + am0.y * uq[1]) + (am0.z * uq[2] + am0.w * uq[3]);
;           part += (am1.x * uq[4] + am1.y * uq[5]) + (am1.z * uq[6] + am1.w * uq[7]);
;           ut = gt - quad_sum(part);
;         }
;         uq[t & 7] = (q == (t >> 3)) ? ut : uq[t & 7];
;         if (t & 1) asm volatile("" : "+v"(o1) : "v"(ut)); else asm volatile("" : "+v"(o0) : "v"(ut));
;       }
.LBB0_2581:
	v_ashrrev_i32_e32 v0, 2, v80
	v_add_u32_e32 v152, v0, v84
	v_and_b32_e32 v153, 3, v80
	v_lshlrev_b32_e32 v154, 2, v152
	v_lshl_add_u32 v155, v153, 11, v154
	v_lshlrev_b32_e32 v0, 5, v153
	ds_read_b32 v18, v155 offset:0
	ds_read_b32 v19, v155 offset:256
	ds_read_b32 v20, v155 offset:512
	ds_read_b32 v21, v155 offset:768
	ds_read_b32 v22, v155 offset:1024
	ds_read_b32 v23, v155 offset:1280
	ds_read_b32 v24, v155 offset:1536
	ds_read_b32 v25, v155 offset:1792
	ds_read_b128 v[26:29], v0 offset:60416
	ds_read_b128 v[30:33], v0 offset:60432
	ds_read_b128 v[156:159], v0 offset:60560
	ds_read_b128 v[160:163], v0 offset:60576
	ds_read_b128 v[170:173], v0 offset:60704
	ds_read_b128 v[174:177], v0 offset:60720
	s_waitcnt lgkmcnt(6)
	ds_read_b128 v[178:181], v0 offset:60848
	ds_read_b128 v[182:185], v0 offset:60864
	ds_read_b128 v[186:189], v0 offset:60992
	ds_read_b128 v[190:193], v0 offset:61008
	ds_read_b128 v[194:197], v0 offset:61136
	ds_read_b128 v[198:201], v0 offset:61152
	s_waitcnt lgkmcnt(10)
	v_mov_b32_dpp v80, v18 quad_perm:[0,0,0,0] row_mask:0xf bank_mask:0xf
	v_pk_fma_f32 v[18:19], v[26:27], v[80:81], v[18:19] op_sel_hi:[1,0,1] neg_lo:[0,1,0] neg_hi:[0,1,0]
	v_pk_fma_f32 v[20:21], v[28:29], v[80:81], v[20:21] op_sel_hi:[1,0,1] neg_lo:[0,1,0] neg_hi:[0,1,0]
	v_pk_fma_f32 v[22:23], v[30:31], v[80:81], v[22:23] op_sel_hi:[1,0,1] neg_lo:[0,1,0] neg_hi:[0,1,0]
	v_pk_fma_f32 v[24:25], v[32:33], v[80:81], v[24:25] op_sel_hi:[1,0,1] neg_lo:[0,1,0] neg_hi:[0,1,0]
	ds_read_b128 v[26:29], v0 offset:61280
	ds_read_b128 v[30:33], v0 offset:61296
	s_waitcnt lgkmcnt(10)
	v_mov_b32_dpp v80, v19 quad_perm:[0,0,0,0] row_mask:0xf bank_mask:0xf
	v_pk_fma_f32 v[20:21], v[158:159], v[80:81], v[20:21] op_sel_hi:[1,0,1] neg_lo:[0,1,0] neg_hi:[0,1,0]
	v_pk_fma_f32 v[18:19], v[156:157], v[80:81], v[18:19] op_sel_hi:[1,0,1] neg_lo:[0,1,0] neg_hi:[0,1,0]
	v_pk_fma_f32 v[22:23], v[160:161], v[80:81], v[22:23] op_sel_hi:[1,0,1] neg_lo:[0,1,0] neg_hi:[0,1,0]
	v_pk_fma_f32 v[24:25], v[162:163], v[80:81], v[24:25] op_sel_hi:[1,0,1] neg_lo:[0,1,0] neg_hi:[0,1,0]
	ds_read_b128 v[156:159], v0 offset:61424
	ds_read_b128 v[160:163], v0 offset:61440
	s_waitcnt lgkmcnt(10)
	v_mov_b32_dpp v80, v20 quad_perm:[0,0,0,0] row_mask:0xf bank_mask:0xf
	v_pk_fma_f32 v[20:21], v[172:173], v[80:81], v[20:21] op_sel_hi:[1,0,1] neg_lo:[0,1,0] neg_hi:[0,1,0]
	v_pk_fma_f32 v[18:19], v[170:171], v[80:81], v[18:19] op_sel_hi:[1,0,1] neg_lo:[0,1,0] neg_hi:[0,1,0]
	v_pk_fma_f32 v[22:23], v[174:175], v[80:81], v[22:23] op_sel_hi:[1,0,1] neg_lo:[0,1,0] neg_hi:[0,1,0]
	v_pk_fma_f32 v[24:25], v[176:177], v[80:81], v[24:25] op_sel_hi:[1,0,1] neg_lo:[0,1,0] neg_hi:[0,1,0]
	ds_read_b128 v[170:173], v0 offset:61568
	ds_read_b128 v[174:177], v0 offset:61584
	s_waitcnt lgkmcnt(10)
	v_mov_b32_dpp v80, v21 quad_perm:[0,0,0,0] row_mask:0xf bank_mask:0xf
	v_pk_fma_f32 v[22:23], v[182:183], v[80:81], v[22:23] op_sel_hi:[1,0,1] neg_lo:[0,1,0] neg_hi:[0,1,0]
	v_pk_fma_f32 v[18:19], v[178:179], v[80:81], v[18:19] op_sel_hi:[1,0,1] neg_lo:[0,1,0] neg_hi:[0,1,0]
	v_pk_fma_f32 v[20:21], v[180:181], v[80:81], v[20:21] op_sel_hi:[1,0,1] neg_lo:[0,1,0] neg_hi:[0,1,0]
	v_pk_fma_f32 v[24:25], v[184:185], v[80:81], v[24:25] op_sel_hi:[1,0,1] neg_lo:[0,1,0] neg_hi:[0,1,0]
	ds_read_b128 v[178:181], v0 offset:61712
	ds_read_b128 v[182:185], v0 offset:61728
	s_waitcnt lgkmcnt(10)
	v_mov_b32_dpp v80, v22 quad_perm:[0,0,0,0] row_mask:0xf bank_mask:0xf
	v_pk_fma_f32 v[22:23], v[190:191], v[80:81], v[22:23] op_sel_hi:[1,0,1] neg_lo:[0,1,0] neg_hi:[0,1,0]
	v_pk_fma_f32 v[18:19], v[186:187], v[80:81], v[18:19] op_sel_hi:[1,0,1] neg_lo:[0,1,0] neg_hi:[0,1,0]
	v_pk_fma_f32 v[20:21], v[188:189], v[80:81], v[20:21] op_sel_hi:[1,0,1] neg_lo:[0,1,0] neg_hi:[0,1,0]
	v_pk_fma_f32 v[24:25], v[192:193], v[80:81], v[24:25] op_sel_hi:[1,0,1] neg_lo:[0,1,0] neg_hi:[0,1,0]
	ds_read_b128 v[186:189], v0 offset:61856
	ds_read_b128 v[190:193], v0 offset:61872
	s_waitcnt lgkmcnt(10)
	v_mov_b32_dpp v80, v23 quad_perm:[0,0,0,0] row_mask:0xf bank_mask:0xf
	v_pk_fma_f32 v[24:25], v[200:201], v[80:81], v[24:25] op_sel_hi:[1,0,1] neg_lo:[0,1,0] neg_hi:[0,1,0]
	v_pk_fma_f32 v[18:19], v[194:195], v[80:81], v[18:19] op_sel_hi:[1,0,1] neg_lo:[0,1,0] neg_hi:[0,1,0]
	v_pk_fma_f32 v[20:21], v[196:197], v[80:81], v[20:21] op_sel_hi:[1,0,1] neg_lo:[0,1,0] neg_hi:[0,1,0]
	v_pk_fma_f32 v[22:23], v[198:199], v[80:81], v[22:23] op_sel_hi:[1,0,1] neg_lo:[0,1,0] neg_hi:[0,1,0]
	ds_read_b128 v[194:197], v0 offset:62000
	ds_read_b128 v[198:201], v0 offset:62016
	s_waitcnt lgkmcnt(10)
	v_mov_b32_dpp v80, v24 quad_perm:[0,0,0,0] row_mask:0xf bank_mask:0xf
	v_pk_fma_f32 v[24:25], v[32:33], v[80:81], v[24:25] op_sel_hi:[1,0,1] neg_lo:[0,1,0] neg_hi:[0,1,0]
	v_pk_fma_f32 v[18:19], v[26:27], v[80:81], v[18:19] op_sel_hi:[1,0,1] neg_lo:[0,1,0] neg_hi:[0,1,0]
	v_pk_fma_f32 v[20:21], v[28:29], v[80:81], v[20:21] op_sel_hi:[1,0,1] neg_lo:[0,1,0] neg_hi:[0,1,0]
	v_pk_fma_f32 v[22:23], v[30:31], v[80:81], v[22:23] op_sel_hi:[1,0,1] neg_lo:[0,1,0] neg_hi:[0,1,0]
	ds_read_b128 v[26:29], v0 offset:62144
	ds_read_b128 v[30:33], v0 offset:62160
	s_waitcnt lgkmcnt(10)
	v_mov_b32_dpp v80, v25 quad_perm:[0,0,0,0] row_mask:0xf bank_mask:0xf
	v_pk_fma_f32 v[18:19], v[156:157], v[80:81], v[18:19] op_sel_hi:[1,0,1] neg_lo:[0,1,0] neg_hi:[0,1,0]
	v_pk_fma_f32 v[20:21], v[158:159], v[80:81], v[20:21] op_sel_hi:[1,0,1] neg_lo:[0,1,0] neg_hi:[0,1,0]
	v_pk_fma_f32 v[22:23], v[160:161], v[80:81], v[22:23] op_sel_hi:[1,0,1] neg_lo:[0,1,0] neg_hi:[0,1,0]
	v_pk_fma_f32 v[24:25], v[162:163], v[80:81], v[24:25] op_sel_hi:[1,0,1] neg_lo:[0,1,0] neg_hi:[0,1,0]
	ds_read_b128 v[156:159], v0 offset:62288
	ds_read_b128 v[160:163], v0 offset:62304
	s_waitcnt lgkmcnt(10)
; DI void scan_chain_c(const P& p, int l, int chain, char* smem, const XcdBarrier* xb, const int* hint, int nhs) {
;     ...
;       for (int t = 0; t < 32; ++t) {
;         const int oo = (t & 1) ? o1 : o0;
;         const float gt = GT[t * 64 + col + oo];
;         float ut = gt;
;         if (t > 0) {
;           const f32x4 am0 = *(const f32x4*)(Am + t * 36 + 8 * q + oo);
;           const f32x4 am1 = *(const f32x4*)(Am + t * 36 + 8 * q + 4 + oo);
;           float part = (am0.x * uq[0] + am0.y * uq[1]) + (am0.z * uq[2] + am0.w * uq[3]);
;           part += (am1.x * uq[4] + am1.y * uq[5]) + (am1.z * uq[6] + am1.w * uq[7]);
;           ut = gt - quad_sum(part);
;         }
;         uq[t & 7] = (q == (t >> 3)) ? ut : uq[t & 7];
;         if (t & 1) asm volatile("" : "+v"(o1) : "v"(ut)); else asm volatile("" : "+v"(o0) : "v"(ut));
	v_mov_b32_dpp v80, v18 quad_perm:[1,1,1,1] row_mask:0xf bank_mask:0xf
	v_pk_fma_f32 v[18:19], v[170:171], v[80:81], v[18:19] op_sel_hi:[1,0,1] neg_lo:[0,1,0] neg_hi:[0,1,0]
	v_pk_fma_f32 v[20:21], v[172:173], v[80:81], v[20:21] op_sel_hi:[1,0,1] neg_lo:[0,1,0] neg_hi:[0,1,0]
	v_pk_fma_f32 v[22:23], v[174:175], v[80:81], v[22:23] op_sel_hi:[1,0,1] neg_lo:[0,1,0] neg_hi:[0,1,0]
	v_pk_fma_f32 v[24:25], v[176:177], v[80:81], v[24:25] op_sel_hi:[1,0,1] neg_lo:[0,1,0] neg_hi:[0,1,0]
	ds_read_b128 v[170:173], v0 offset:62432
	ds_read_b128 v[174:177], v0 offset:62448
	s_waitcnt lgkmcnt(10)
	v_mov_b32_dpp v80, v19 quad_perm:[1,1,1,1] row_mask:0xf bank_mask:0xf
	v_pk_fma_f32 v[20:21], v[180:181], v[80:81], v[20:21] op_sel_hi:[1,0,1] neg_lo:[0,1,0] neg_hi:[0,1,0]
	v_pk_fma_f32 v[18:19], v[178:179], v[80:81], v[18:19] op_sel_hi:[1,0,1] neg_lo:[0,1,0] neg_hi:[0,1,0]
	v_pk_fma_f32 v[22:23], v[182:183], v[80:81], v[22:23] op_sel_hi:[1,0,1] neg_lo:[0,1,0] neg_hi:[0,1,0]
	v_pk_fma_f32 v[24:25], v[184:185], v[80:81], v[24:25] op_sel_hi:[1,0,1] neg_lo:[0,1,0] neg_hi:[0,1,0]
	ds_read_b128 v[178:181], v0 offset:62576
	ds_read_b128 v[182:185], v0 offset:62592
	s_waitcnt lgkmcnt(10)
	v_mov_b32_dpp v80, v20 quad_perm:[1,1,1,1] row_mask:0xf bank_mask:0xf
	v_pk_fma_f32 v[20:21], v[188:189], v[80:81], v[20:21] op_sel_hi:[1,0,1] neg_lo:[0,1,0] neg_hi:[0,1,0]
	v_pk_fma_f32 v[18:19], v[186:187], v[80:81], v[18:19] op_sel_hi:[1,0,1] neg_lo:[0,1,0] neg_hi:[0,1,0]
	v_pk_fma_f32 v[22:23], v[190:191], v[80:81], v[22:23] op_sel_hi:[1,0,1] neg_lo:[0,1,0] neg_hi:[0,1,0]
	v_pk_fma_f32 v[24:25], v[192:193], v[80:81], v[24:25] op_sel_hi:[1,0,1] neg_lo:[0,1,0] neg_hi:[0,1,0]
	ds_read_b128 v[186:189], v0 offset:62720
	ds_read_b128 v[190:193], v0 offset:62736
	s_waitcnt lgkmcnt(10)
	v_mov_b32_dpp v80, v21 quad_perm:[1,1,1,1] row_mask:0xf bank_mask:0xf
	v_pk_fma_f32 v[22:23], v[198:199], v[80:81], v[22:23] op_sel_hi:[1,0,1] neg_lo:[0,1,0] neg_hi:[0,1,0]
	v_pk_fma_f32 v[18:19], v[194:195], v[80:81], v[18:19] op_sel_hi:[1,0,1] neg_lo:[0,1,0] neg_hi:[0,1,0]
	v_pk_fma_f32 v[20:21], v[196:197], v[80:81], v[20:21] op_sel_hi:[1,0,1] neg_lo:[0,1,0] neg_hi:[0,1,0]
	v_pk_fma_f32 v[24:25], v[200:201], v[80:81], v[24:25] op_sel_hi:[1,0,1] neg_lo:[0,1,0] neg_hi:[0,1,0]
	ds_read_b128 v[194:197], v0 offset:62864
	ds_read_b128 v[198:201], v0 offset:62880
	s_waitcnt lgkmcnt(10)
	v_mov_b32_dpp v80, v22 quad_perm:[1,1,1,1] row_mask:0xf bank_mask:0xf
	v_pk_fma_f32 v[22:23], v[30:31], v[80:81], v[22:23] op_sel_hi:[1,0,1] neg_lo:[0,1,0] neg_hi:[0,1,0]
	v_pk_fma_f32 v[18:19], v[26:27], v[80:81], v[18:19] op_sel_hi:[1,0,1] neg_lo:[0,1,0] neg_hi:[0,1,0]
	v_pk_fma_f32 v[20:21], v[28:29], v[80:81], v[20:21] op_sel_hi:[1,0,1] neg_lo:[0,1,0] neg_hi:[0,1,0]
	v_pk_fma_f32 v[24:25], v[32:33], v[80:81], v[24:25] op_sel_hi:[1,0,1] neg_lo:[0,1,0] neg_hi:[0,1,0]
	ds_read_b128 v[26:29], v0 offset:63008
	ds_read_b128 v[30:33], v0 offset:63024
	s_waitcnt lgkmcnt(10)
	v_mov_b32_dpp v80, v23 quad_perm:[1,1,1,1] row_mask:0xf bank_mask:0xf
	v_pk_fma_f32 v[24:25], v[162:163], v[80:81], v[24:25] op_sel_hi:[1,0,1] neg_lo:[0,1,0] neg_hi:[0,1,0]
	v_pk_fma_f32 v[18:19], v[156:157], v[80:81], v[18:19] op_sel_hi:[1,0,1] neg_lo:[0,1,0] neg_hi:[0,1,0]
	v_pk_fma_f32 v[20:21], v[158:159], v[80:81], v[20:21] op_sel_hi:[1,0,1] neg_lo:[0,1,0] neg_hi:[0,1,0]
	v_pk_fma_f32 v[22:23], v[160:161], v[80:81], v[22:23] op_sel_hi:[1,0,1] neg_lo:[0,1,0] neg_hi:[0,1,0]
	ds_read_b128 v[156:159], v0 offset:63152
	ds_read_b128 v[160:163], v0 offset:63168
	s_waitcnt lgkmcnt(10)
	v_mov_b32_dpp v80, v24 quad_perm:[1,1,1,1] row_mask:0xf bank_mask:0xf
	v_pk_fma_f32 v[24:25], v[176:177], v[80:81], v[24:25] op_sel_hi:[1,0,1] neg_lo:[0,1,0] neg_hi:[0,1,0]
	v_pk_fma_f32 v[18:19], v[170:171], v[80:81], v[18:19] op_sel_hi:[1,0,1] neg_lo:[0,1,0] neg_hi:[0,1,0]
	v_pk_fma_f32 v[20:21], v[172:173], v[80:81], v[20:21] op_sel_hi:[1,0,1] neg_lo:[0,1,0] neg_hi:[0,1,0]
	v_pk_fma_f32 v[22:23], v[174:175], v[80:81], v[22:23] op_sel_hi:[1,0,1] neg_lo:[0,1,0] neg_hi:[0,1,0]
	ds_read_b128 v[170:173], v0 offset:63296
	ds_read_b128 v[174:177], v0 offset:63312
	s_waitcnt lgkmcnt(10)
	v_mov_b32_dpp v80, v25 quad_perm:[1,1,1,1] row_mask:0xf bank_mask:0xf
	v_pk_fma_f32 v[18:19], v[178:179], v[80:81], v[18:19] op_sel_hi:[1,0,1] neg_lo:[0,1,0] neg_hi:[0,1,0]
	v_pk_fma_f32 v[20:21], v[180:181], v[80:81], v[20:21] op_sel_hi:[1,0,1] neg_lo:[0,1,0] neg_hi:[0,1,0]
	v_pk_fma_f32 v[22:23], v[182:183], v[80:81], v[22:23] op_sel_hi:[1,0,1] neg_lo:[0,1,0] neg_hi:[0,1,0]
	v_pk_fma_f32 v[24:25], v[184:185], v[80:81], v[24:25] op_sel_hi:[1,0,1] neg_lo:[0,1,0] neg_hi:[0,1,0]
	ds_read_b128 v[178:181], v0 offset:63440
	ds_read_b128 v[182:185], v0 offset:63456
	s_waitcnt lgkmcnt(10)
	v_mov_b32_dpp v80, v18 quad_perm:[2,2,2,2] row_mask:0xf bank_mask:0xf
	v_pk_fma_f32 v[18:19], v[186:187], v[80:81], v[18:19] op_sel_hi:[1,0,1] neg_lo:[0,1,0] neg_hi:[0,1,0]
	v_pk_fma_f32 v[20:21], v[188:189], v[80:81], v[20:21] op_sel_hi:[1,0,1] neg_lo:[0,1,0] neg_hi:[0,1,0]
	v_pk_fma_f32 v[22:23], v[190:191], v[80:81], v[22:23] op_sel_hi:[1,0,1] neg_lo:[0,1,0] neg_hi:[0,1,0]
	v_pk_fma_f32 v[24:25], v[192:193], v[80:81], v[24:25] op_sel_hi:[1,0,1] neg_lo:[0,1,0] neg_hi:[0,1,0]
	ds_read_b128 v[186:189], v0 offset:63584
	ds_read_b128 v[190:193], v0 offset:63600
	s_waitcnt lgkmcnt(10)
	v_mov_b32_dpp v80, v19 quad_perm:[2,2,2,2] row_mask:0xf bank_mask:0xf
	v_pk_fma_f32 v[20:21], v[196:197], v[80:81], v[20:21] op_sel_hi:[1,0,1] neg_lo:[0,1,0] neg_hi:[0,1,0]
	v_pk_fma_f32 v[18:19], v[194:195], v[80:81], v[18:19] op_sel_hi:[1,0,1] neg_lo:[0,1,0] neg_hi:[0,1,0]
	v_pk_fma_f32 v[22:23], v[198:199], v[80:81], v[22:23] op_sel_hi:[1,0,1] neg_lo:[0,1,0] neg_hi:[0,1,0]
	v_pk_fma_f32 v[24:25], v[200:201], v[80:81], v[24:25] op_sel_hi:[1,0,1] neg_lo:[0,1,0] neg_hi:[0,1,0]
	ds_read_b128 v[194:197], v0 offset:63728
	ds_read_b128 v[198:201], v0 offset:63744
	s_waitcnt lgkmcnt(10)
; DI void scan_chain_c(const P& p, int l, int chain, char* smem, const XcdBarrier* xb, const int* hint, int nhs) {
;     ...
;       for (int t = 0; t < 32; ++t) {
;         const int oo = (t & 1) ? o1 : o0;
;         const float gt = GT[t * 64 + col + oo];
;         float ut = gt;
;         if (t > 0) {
;           const f32x4 am0 = *(const f32x4*)(Am + t * 36 + 8 * q + oo);
;           const f32x4 am1 = *(const f32x4*)(Am + t * 36 + 8 * q + 4 + oo);
;           float part = (am0.x * uq[0] + am0.y * uq[1]) + (am0.z * uq[2] + am0.w * uq[3]);
;           part += (am1.x * uq[4] + am1.y * uq[5]) + (am1.z * uq[6] + am1.w * uq[7]);
;           ut = gt - quad_sum(part);
;         }
;         uq[t & 7] = (q == (t >> 3)) ? ut : uq[t & 7];
;         if (t & 1) asm volatile("" : "+v"(o1) : "v"(ut)); else asm volatile("" : "+v"(o0) : "v"(ut));
	v_mov_b32_dpp v80, v20 quad_perm:[2,2,2,2] row_mask:0xf bank_mask:0xf
	v_pk_fma_f32 v[20:21], v[28:29], v[80:81], v[20:21] op_sel_hi:[1,0,1] neg_lo:[0,1,0] neg_hi:[0,1,0]
	v_pk_fma_f32 v[18:19], v[26:27], v[80:81], v[18:19] op_sel_hi:[1,0,1] neg_lo:[0,1,0] neg_hi:[0,1,0]
	v_pk_fma_f32 v[22:23], v[30:31], v[80:81], v[22:23] op_sel_hi:[1,0,1] neg_lo:[0,1,0] neg_hi:[0,1,0]
	v_pk_fma_f32 v[24:25], v[32:33], v[80:81], v[24:25] op_sel_hi:[1,0,1] neg_lo:[0,1,0] neg_hi:[0,1,0]
	ds_read_b128 v[26:29], v0 offset:63872
	ds_read_b128 v[30:33], v0 offset:63888
	s_waitcnt lgkmcnt(10)
	v_mov_b32_dpp v80, v21 quad_perm:[2,2,2,2] row_mask:0xf bank_mask:0xf
	v_pk_fma_f32 v[22:23], v[160:161], v[80:81], v[22:23] op_sel_hi:[1,0,1] neg_lo:[0,1,0] neg_hi:[0,1,0]
	v_pk_fma_f32 v[18:19], v[156:157], v[80:81], v[18:19] op_sel_hi:[1,0,1] neg_lo:[0,1,0] neg_hi:[0,1,0]
	v_pk_fma_f32 v[20:21], v[158:159], v[80:81], v[20:21] op_sel_hi:[1,0,1] neg_lo:[0,1,0] neg_hi:[0,1,0]
	v_pk_fma_f32 v[24:25], v[162:163], v[80:81], v[24:25] op_sel_hi:[1,0,1] neg_lo:[0,1,0] neg_hi:[0,1,0]
	ds_read_b128 v[156:159], v0 offset:64016
	ds_read_b128 v[160:163], v0 offset:64032
	s_waitcnt lgkmcnt(10)
	v_mov_b32_dpp v80, v22 quad_perm:[2,2,2,2] row_mask:0xf bank_mask:0xf
	v_pk_fma_f32 v[22:23], v[174:175], v[80:81], v[22:23] op_sel_hi:[1,0,1] neg_lo:[0,1,0] neg_hi:[0,1,0]
	v_pk_fma_f32 v[18:19], v[170:171], v[80:81], v[18:19] op_sel_hi:[1,0,1] neg_lo:[0,1,0] neg_hi:[0,1,0]
	v_pk_fma_f32 v[20:21], v[172:173], v[80:81], v[20:21] op_sel_hi:[1,0,1] neg_lo:[0,1,0] neg_hi:[0,1,0]
	v_pk_fma_f32 v[24:25], v[176:177], v[80:81], v[24:25] op_sel_hi:[1,0,1] neg_lo:[0,1,0] neg_hi:[0,1,0]
	ds_read_b128 v[170:173], v0 offset:64160
	ds_read_b128 v[174:177], v0 offset:64176
	s_waitcnt lgkmcnt(10)
	v_mov_b32_dpp v80, v23 quad_perm:[2,2,2,2] row_mask:0xf bank_mask:0xf
	v_pk_fma_f32 v[24:25], v[184:185], v[80:81], v[24:25] op_sel_hi:[1,0,1] neg_lo:[0,1,0] neg_hi:[0,1,0]
	v_pk_fma_f32 v[18:19], v[178:179], v[80:81], v[18:19] op_sel_hi:[1,0,1] neg_lo:[0,1,0] neg_hi:[0,1,0]
	v_pk_fma_f32 v[20:21], v[180:181], v[80:81], v[20:21] op_sel_hi:[1,0,1] neg_lo:[0,1,0] neg_hi:[0,1,0]
	v_pk_fma_f32 v[22:23], v[182:183], v[80:81], v[22:23] op_sel_hi:[1,0,1] neg_lo:[0,1,0] neg_hi:[0,1,0]
	ds_read_b128 v[178:181], v0 offset:64304
	ds_read_b128 v[182:185], v0 offset:64320
	s_waitcnt lgkmcnt(10)
	v_mov_b32_dpp v80, v24 quad_perm:[2,2,2,2] row_mask:0xf bank_mask:0xf
	v_pk_fma_f32 v[24:25], v[192:193], v[80:81], v[24:25] op_sel_hi:[1,0,1] neg_lo:[0,1,0] neg_hi:[0,1,0]
	v_pk_fma_f32 v[18:19], v[186:187], v[80:81], v[18:19] op_sel_hi:[1,0,1] neg_lo:[0,1,0] neg_hi:[0,1,0]
	v_pk_fma_f32 v[20:21], v[188:189], v[80:81], v[20:21] op_sel_hi:[1,0,1] neg_lo:[0,1,0] neg_hi:[0,1,0]
	v_pk_fma_f32 v[22:23], v[190:191], v[80:81], v[22:23] op_sel_hi:[1,0,1] neg_lo:[0,1,0] neg_hi:[0,1,0]
	ds_read_b128 v[186:189], v0 offset:64448
	ds_read_b128 v[190:193], v0 offset:64464
	s_waitcnt lgkmcnt(10)
	v_mov_b32_dpp v80, v25 quad_perm:[2,2,2,2] row_mask:0xf bank_mask:0xf
	v_pk_fma_f32 v[18:19], v[194:195], v[80:81], v[18:19] op_sel_hi:[1,0,1] neg_lo:[0,1,0] neg_hi:[0,1,0]
	v_pk_fma_f32 v[20:21], v[196:197], v[80:81], v[20:21] op_sel_hi:[1,0,1] neg_lo:[0,1,0] neg_hi:[0,1,0]
	v_pk_fma_f32 v[22:23], v[198:199], v[80:81], v[22:23] op_sel_hi:[1,0,1] neg_lo:[0,1,0] neg_hi:[0,1,0]
	v_pk_fma_f32 v[24:25], v[200:201], v[80:81], v[24:25] op_sel_hi:[1,0,1] neg_lo:[0,1,0] neg_hi:[0,1,0]
	ds_read_b128 v[194:197], v0 offset:64592
	ds_read_b128 v[198:201], v0 offset:64608
	s_waitcnt lgkmcnt(10)
	v_mov_b32_dpp v80, v18 quad_perm:[3,3,3,3] row_mask:0xf bank_mask:0xf
	v_pk_fma_f32 v[18:19], v[26:27], v[80:81], v[18:19] op_sel_hi:[1,0,1] neg_lo:[0,1,0] neg_hi:[0,1,0]
	v_pk_fma_f32 v[20:21], v[28:29], v[80:81], v[20:21] op_sel_hi:[1,0,1] neg_lo:[0,1,0] neg_hi:[0,1,0]
	v_pk_fma_f32 v[22:23], v[30:31], v[80:81], v[22:23] op_sel_hi:[1,0,1] neg_lo:[0,1,0] neg_hi:[0,1,0]
	v_pk_fma_f32 v[24:25], v[32:33], v[80:81], v[24:25] op_sel_hi:[1,0,1] neg_lo:[0,1,0] neg_hi:[0,1,0]
	ds_read_b128 v[26:29], v0 offset:64736
	ds_read_b128 v[30:33], v0 offset:64752
	s_waitcnt lgkmcnt(10)
; #define L(ph, l, hf) hipLaunchKernelGGL(k_phase<ph>, dim3(G), dim3(256), 0, stream, p, l, hf)
; DI void scan_chain_c(const P& p, int l, int chain, char* smem, const XcdBarrier* xb, const int* hint, int nhs) {
;     ...
;   auto prefetch = [&](int n0) {
;     const bool lat = n0 >= 256;
;     const int L = lat ? 4096 : 256;
;     const int rowbase = lat ? b * 4096 : TL + b * 256;
;     const int nn = (lat ? n0 - 256 : n0);
;     const int P0 = d ? (L - 1 - (nn + 8 * w)) : (nn + 8 * w);
; #pragma unroll
;     for (int q = 0; q < 10; ++q) {
;       const int pq = d ? (P0 + 1 - q) : (P0 - 1 + q);
;       h16 a_ = (h16)0.f, b_ = (h16)0.f, c_ = (h16)0.f;
;       if (pq >= 0 && pq < L) {
;         const h16* x1 = rkv + (size_t)(rowbase + pq) * 1536 + c;
;         a_ = x1[0]; b_ = x1[512]; c_ = x1[1024];
;       }
;       xr[q] = a_; xk[q] = b_; xv[q] = c_;
;     }
;     ...
;       for (int t = 0; t < 32; ++t) {
;         const int oo = (t & 1) ? o1 : o0;
;         const float gt = GT[t * 64 + col + oo];
;         float ut = gt;
;         if (t > 0) {
;           const f32x4 am0 = *(const f32x4*)(Am + t * 36 + 8 * q + oo);
;           const f32x4 am1 = *(const f32x4*)(Am + t * 36 + 8 * q + 4 + oo);
;           float part = (am0.x * uq[0] + am0.y * uq[1]) + (am0.z * uq[2] + am0.w * uq[3]);
;           part += (am1.x * uq[4] + am1.y * uq[5]) + (am1.z * uq[6] + am1.w * uq[7]);
;           ut = gt - quad_sum(part);
;         }
;         uq[t & 7] = (q == (t >> 3)) ? ut : uq[t & 7];
;         if (t & 1) asm volatile("" : "+v"(o1) : "v"(ut)); else asm volatile("" : "+v"(o0) : "v"(ut));
;       }
;       b16x8 o;
; #pragma unroll
;       for (int e = 0; e < 8; ++e) o[e] = (b16)uq[e];
;       *(b16x8*)(UTt + col * 40 + 8 * q) = o;
;       if (n0 + 32 < 256 + 4096) prefetch(n0 + 32);
	v_mov_b32_dpp v80, v19 quad_perm:[3,3,3,3] row_mask:0xf bank_mask:0xf
	v_pk_fma_f32 v[20:21], v[158:159], v[80:81], v[20:21] op_sel_hi:[1,0,1] neg_lo:[0,1,0] neg_hi:[0,1,0]
	v_pk_fma_f32 v[18:19], v[156:157], v[80:81], v[18:19] op_sel_hi:[1,0,1] neg_lo:[0,1,0] neg_hi:[0,1,0]
	v_pk_fma_f32 v[22:23], v[160:161], v[80:81], v[22:23] op_sel_hi:[1,0,1] neg_lo:[0,1,0] neg_hi:[0,1,0]
	v_pk_fma_f32 v[24:25], v[162:163], v[80:81], v[24:25] op_sel_hi:[1,0,1] neg_lo:[0,1,0] neg_hi:[0,1,0]
	s_waitcnt lgkmcnt(8)
	v_mov_b32_dpp v80, v20 quad_perm:[3,3,3,3] row_mask:0xf bank_mask:0xf
	v_pk_fma_f32 v[20:21], v[172:173], v[80:81], v[20:21] op_sel_hi:[1,0,1] neg_lo:[0,1,0] neg_hi:[0,1,0]
	v_pk_fma_f32 v[18:19], v[170:171], v[80:81], v[18:19] op_sel_hi:[1,0,1] neg_lo:[0,1,0] neg_hi:[0,1,0]
	v_pk_fma_f32 v[22:23], v[174:175], v[80:81], v[22:23] op_sel_hi:[1,0,1] neg_lo:[0,1,0] neg_hi:[0,1,0]
	v_pk_fma_f32 v[24:25], v[176:177], v[80:81], v[24:25] op_sel_hi:[1,0,1] neg_lo:[0,1,0] neg_hi:[0,1,0]
	s_waitcnt lgkmcnt(6)
	v_mov_b32_dpp v80, v21 quad_perm:[3,3,3,3] row_mask:0xf bank_mask:0xf
	v_pk_fma_f32 v[22:23], v[182:183], v[80:81], v[22:23] op_sel_hi:[1,0,1] neg_lo:[0,1,0] neg_hi:[0,1,0]
	v_pk_fma_f32 v[18:19], v[178:179], v[80:81], v[18:19] op_sel_hi:[1,0,1] neg_lo:[0,1,0] neg_hi:[0,1,0]
	v_pk_fma_f32 v[20:21], v[180:181], v[80:81], v[20:21] op_sel_hi:[1,0,1] neg_lo:[0,1,0] neg_hi:[0,1,0]
	v_pk_fma_f32 v[24:25], v[184:185], v[80:81], v[24:25] op_sel_hi:[1,0,1] neg_lo:[0,1,0] neg_hi:[0,1,0]
	s_waitcnt lgkmcnt(4)
	v_mov_b32_dpp v80, v22 quad_perm:[3,3,3,3] row_mask:0xf bank_mask:0xf
	v_pk_fma_f32 v[22:23], v[190:191], v[80:81], v[22:23] op_sel_hi:[1,0,1] neg_lo:[0,1,0] neg_hi:[0,1,0]
	v_pk_fma_f32 v[18:19], v[186:187], v[80:81], v[18:19] op_sel_hi:[1,0,1] neg_lo:[0,1,0] neg_hi:[0,1,0]
	v_pk_fma_f32 v[20:21], v[188:189], v[80:81], v[20:21] op_sel_hi:[1,0,1] neg_lo:[0,1,0] neg_hi:[0,1,0]
	v_pk_fma_f32 v[24:25], v[192:193], v[80:81], v[24:25] op_sel_hi:[1,0,1] neg_lo:[0,1,0] neg_hi:[0,1,0]
	s_waitcnt lgkmcnt(2)
	v_mov_b32_dpp v80, v23 quad_perm:[3,3,3,3] row_mask:0xf bank_mask:0xf
	v_pk_fma_f32 v[24:25], v[200:201], v[80:81], v[24:25] op_sel_hi:[1,0,1] neg_lo:[0,1,0] neg_hi:[0,1,0]
	v_pk_fma_f32 v[18:19], v[194:195], v[80:81], v[18:19] op_sel_hi:[1,0,1] neg_lo:[0,1,0] neg_hi:[0,1,0]
	v_pk_fma_f32 v[20:21], v[196:197], v[80:81], v[20:21] op_sel_hi:[1,0,1] neg_lo:[0,1,0] neg_hi:[0,1,0]
	v_pk_fma_f32 v[22:23], v[198:199], v[80:81], v[22:23] op_sel_hi:[1,0,1] neg_lo:[0,1,0] neg_hi:[0,1,0]
	s_waitcnt lgkmcnt(0)
	v_mov_b32_dpp v80, v24 quad_perm:[3,3,3,3] row_mask:0xf bank_mask:0xf
	v_pk_fma_f32 v[24:25], v[32:33], v[80:81], v[24:25] op_sel_hi:[1,0,1] neg_lo:[0,1,0] neg_hi:[0,1,0]
	v_pk_fma_f32 v[18:19], v[26:27], v[80:81], v[18:19] op_sel_hi:[1,0,1] neg_lo:[0,1,0] neg_hi:[0,1,0]
	v_pk_fma_f32 v[20:21], v[28:29], v[80:81], v[20:21] op_sel_hi:[1,0,1] neg_lo:[0,1,0] neg_hi:[0,1,0]
	v_pk_fma_f32 v[22:23], v[30:31], v[80:81], v[22:23] op_sel_hi:[1,0,1] neg_lo:[0,1,0] neg_hi:[0,1,0]
	v_cvt_pk_bf16_f32 v18, v18, v19
	v_cvt_pk_bf16_f32 v19, v20, v21
	v_cvt_pk_bf16_f32 v20, v22, v23
	v_cvt_pk_bf16_f32 v21, v24, v25
	v_mul_lo_u32 v0, v152, s76
	v_lshl_add_u32 v0, v153, 4, v0
	s_andn2_b64 vcc, exec, s[12:13]
	ds_write_b128 v0, v[18:21] offset:8192
	s_cbranch_vccnz .LBB0_2603
	s_add_i32 s12, s25, 0xffffff20
	s_cmpk_gt_u32 s25, 0xdf
	s_cselect_b32 s12, s12, s26
	s_cselect_b32 s15, s65, 0x100
	v_add_u32_e32 v20, s12, v86
	v_xad_u32 v18, v20, -1, s15
	v_cndmask_b32_e64 v0, v18, v20, s[38:39]
	v_add_u32_e32 v19, 1, v0
	v_add_u32_e32 v20, -1, v20
	v_cndmask_b32_e64 v20, v19, v20, s[38:39]
	s_cselect_b32 s14, s70, s31
	v_cmp_gt_u32_e32 vcc, s15, v20
	v_mov_b32_e32 v87, 0
	v_mov_b32_e32 v88, 0
	v_mov_b32_e32 v89, 0
	v_mov_b32_e32 v90, 0
	s_and_saveexec_b64 s[12:13], vcc
	s_cbranch_execz .LBB0_2584
	v_add_u32_e32 v20, s14, v20
	s_movk_i32 s16, 0xc00
	v_mad_u64_u32 v[20:21], s[16:17], v20, s16, v[70:71]
	global_load_ushort v88, v[20:21], off
	global_load_ushort v89, v[20:21], off offset:1024
	global_load_ushort v90, v[20:21], off offset:2048
